# plus batch-major dilated unit order, EpiBf16/EpiRes/EpiConv epilogue loads hoisted with counted waits, GLA out-phase loads batched
# speedup vs baseline: 1.0144x; 1.0059x over previous
;     __device__ __forceinline__ void operator()(const f32x4 (&acc)[2][2][4][2], const Unit& u, int wr, int wc, int fr, int fq) const {
;     ...
;         float rs[2][4];
; #pragma unroll
;         for (int ai = 0; ai < 2; ++ai)
; #pragma unroll
;             for (int m = 0; m < 4; ++m) rs[ai][m] = __builtin_amdgcn_rsqf((float)ss[u.pm * BM + ai * HALF + wr * 64 + m * 16 + fr] * (1.f / (2048.f * 262144.f)) + 1e-6f);
; #pragma unroll
;         for (int n = 0; n < 2; ++n) {
;             const int cbase = 128 * u.pn + 32 * wc + 16 * n + 4 * fq;
;             const f32x4 w0 = *(const f32x4*)(cw + cbase), w1 = *(const f32x4*)(cw + FF + cbase), w2 = *(const f32x4*)(cw + 2 * FF + cbase), b4 = *(const f32x4*)(cb + cbase);
; #pragma unroll
;             for (int ai = 0; ai < 2; ++ai) {
;                 const int slab = u.pm * 4 + 2 * ai + wr;
;                 f32x4 r1p = (f32x4){0.f, 0.f, 0.f, 0.f}, r2p = (f32x4){0.f, 0.f, 0.f, 0.f};
; #pragma unroll
;                 for (int m = 0; m < 4; ++m) {
;                     const f32x4 g = acc[ai][1][m][n] * rs[ai][m], v = acc[ai][0][m][n] * rs[ai][m];
.LBB0_41:
	v_lshl_add_u32 v160, s66, 8, v193
	v_ashrrev_i32_e32 v161, 31, v160
	v_mov_b32_e32 v148, v227
	v_lshl_add_u64 v[114:115], v[160:161], 3, s[56:57]
	global_load_dwordx2 v[146:147], v[114:115], off
	v_lshl_or_b32 v156, s64, 7, v198
	v_ashrrev_i32_e32 v157, 31, v156
	global_load_dwordx2 v[190:191], v[114:115], off offset:128
	global_load_dwordx2 v[188:189], v[114:115], off offset:256
	global_load_dwordx2 v[186:187], v[114:115], off offset:384
	global_load_dwordx2 v[176:177], v[114:115], off offset:1024
	global_load_dwordx2 v[174:175], v[114:115], off offset:1152
	global_load_dwordx2 v[172:173], v[114:115], off offset:1280
	global_load_dwordx2 v[170:171], v[114:115], off offset:1408
	v_lshlrev_b64 v[158:159], 2, v[156:157]
	v_lshl_add_u64 v[166:167], s[52:53], 0, v[158:159]
	v_lshl_add_u64 v[118:119], s[60:61], 0, v[158:159]
	v_lshl_add_u64 v[120:121], s[62:63], 0, v[158:159]
	v_lshl_add_u64 v[164:165], s[54:55], 0, v[158:159]
	global_load_dwordx4 v[114:117], v[166:167], off
	global_load_dwordx4 v[138:141], v[118:119], off
	global_load_dwordx4 v[130:133], v[120:121], off
	global_load_dwordx4 v[208:211], v[166:167], off offset:64
	global_load_dwordx4 v[212:215], v[118:119], off offset:64
	global_load_dwordx4 v[216:219], v[120:121], off offset:64
	global_load_dwordx4 v[220:223], v[164:165], off offset:64
	s_nop 0
	global_load_dwordx4 v[118:121], v[164:165], off
	s_waitcnt vmcnt(0)
	v_ffbh_u32_e32 v149, v147
	v_min_u32_e32 v149, 32, v149
	v_lshlrev_b64 v[146:147], v149, v[146:147]
	v_min_u32_e32 v146, 1, v146
	v_or_b32_e32 v146, v147, v146
	v_cvt_f32_u32_e32 v146, v146
	v_sub_u32_e32 v149, 32, v149
	v_and_b32_e32 v147, 48, v148
	v_or3_b32 v148, v147, v195, v236
	v_ldexp_f32 v146, v146, v149
	v_fmamk_f32 v146, v146, 0x31000000, v232
	v_rsq_f32_e32 v162, v146
	v_or3_b32 v146, v147, v196, v236
	v_lshlrev_b32_e32 v200, 2, v146
	v_lshlrev_b32_e32 v161, 2, v148
	v_pk_mul_f32 v[146:147], v[134:135], v[162:163] op_sel_hi:[1,0]
	v_pk_mul_f32 v[148:149], v[136:137], v[162:163] op_sel_hi:[1,0]
	ds_bpermute_b32 v163, v200, v146
	ds_bpermute_b32 v179, v161, v146
	ds_bpermute_b32 v181, v161, v147
	ds_bpermute_b32 v201, v200, v147
	ds_bpermute_b32 v183, v161, v148
	ds_bpermute_b32 v202, v200, v148
	ds_bpermute_b32 v185, v161, v149
	ds_bpermute_b32 v203, v200, v149
	s_waitcnt lgkmcnt(7)
	v_pk_mul_f32 v[136:137], v[144:145], v[162:163] op_sel_hi:[1,0]
	v_pk_mul_f32 v[134:135], v[142:143], v[162:163] op_sel_hi:[1,0]
	s_and_saveexec_b64 s[10:11], s[42:43]
	s_xor_b64 s[10:11], exec, s[10:11]
	s_movk_i32 s17, 0x2b00
	s_movk_i32 s84, 0x300
	s_mov_b32 s86, 0x24000
	s_mov_b32 s88, 0x48800000
	s_cbranch_execz .LBB0_43
	v_mov_b32_e32 v142, v149
	v_mov_b32_e32 v143, v141
	v_mov_b32_e32 v184, v133
	s_waitcnt lgkmcnt(1)
	v_pk_mul_f32 v[142:143], v[142:143], v[184:185]
	s_waitcnt lgkmcnt(0)
	v_fma_f32 v144, v117, v203, v121
	v_add_f32_e32 v143, v143, v144
	v_add_f32_e32 v142, v142, v143
	v_mul_f32_e32 v143, 0xbfb8aa3b, v142
	v_exp_f32_e32 v143, v143
	v_mov_b32_e32 v149, v140
	v_mov_b32_e32 v182, v132
	v_mov_b32_e32 v180, v131
	v_add_f32_e32 v143, 1.0, v143
	v_rcp_f32_e32 v143, v143
	v_mov_b32_e32 v178, v130
	v_mul_f32_e32 v142, v142, v143
	v_mul_f32_e32 v144, v137, v142
	v_pk_mul_f32 v[142:143], v[148:149], v[182:183]
	v_fma_f32 v137, v116, v202, v120
	v_add_f32_e32 v137, v143, v137
	v_add_f32_e32 v137, v142, v137
	v_mul_f32_e32 v142, 0xbfb8aa3b, v137
	v_exp_f32_e32 v142, v142
	v_fma_f32 v143, v115, v201, v119
	v_add_f32_e32 v142, 1.0, v142
	v_rcp_f32_e32 v142, v142
	s_nop 0
	v_mul_f32_e32 v137, v137, v142
	v_mul_f32_e32 v142, v136, v137
	v_mov_b32_e32 v136, v147
	v_mov_b32_e32 v137, v139
	v_pk_mul_f32 v[136:137], v[136:137], v[180:181]
	v_mov_b32_e32 v147, v138
	v_add_f32_e32 v137, v137, v143
	v_add_f32_e32 v136, v136, v137
	v_mul_f32_e32 v137, 0xbfb8aa3b, v136
	v_exp_f32_e32 v137, v137
	v_fma_f32 v143, v114, v163, v118
	v_add_f32_e32 v137, 1.0, v137
	v_rcp_f32_e32 v137, v137
	s_nop 0
	v_mul_f32_e32 v136, v136, v137
	v_mul_f32_e32 v135, v135, v136
	v_pk_mul_f32 v[136:137], v[146:147], v[178:179]
	s_nop 0
	v_add_f32_e32 v137, v137, v143
	v_add_f32_e32 v136, v136, v137
	v_mul_f32_e32 v137, 0xbfb8aa3b, v136
	v_exp_f32_e32 v137, v137
	s_nop 0
	v_add_f32_e32 v137, 1.0, v137
	v_rcp_f32_e32 v137, v137
	s_nop 0
	v_mul_f32_e32 v136, v136, v137
	v_mul_f32_e32 v134, v134, v136
	v_mov_b64_e32 v[136:137], s[48:49]
	v_mad_i64_i32 v[136:137], s[12:13], v160, s17, v[136:137]
	v_cvt_pk_bf16_f32 v134, v134, v135
	v_cvt_pk_bf16_f32 v135, v142, v144
	v_lshl_add_u64 v[136:137], v[156:157], 1, v[136:137]
	global_store_dwordx2 v[136:137], v[134:135], off

; __device__ __forceinline__ unsigned cvt_pk_bf16(float lo, float hi) { unsigned r; asm volatile("v_cvt_pk_bf16_f32 %0, %1, %2" : "=v"(r) : "v"(lo), "v"(hi)); return r; }
;     __device__ __forceinline__ void operator()(const f32x4 (&acc)[2][2][4][2], const Unit& u, int wr, int wc, int fr, int fq) const {
;     ...
;         for (int n = 0; n < 2; ++n) {
;             const int cbase = 128 * u.pn + 32 * wc + 16 * n + 4 * fq;
;             const f32x4 w0 = *(const f32x4*)(cw + cbase), w1 = *(const f32x4*)(cw + FF + cbase), w2 = *(const f32x4*)(cw + 2 * FF + cbase), b4 = *(const f32x4*)(cb + cbase);
; #pragma unroll
;             for (int ai = 0; ai < 2; ++ai) {
;                 const int slab = u.pm * 4 + 2 * ai + wr;
;                 f32x4 r1p = (f32x4){0.f, 0.f, 0.f, 0.f}, r2p = (f32x4){0.f, 0.f, 0.f, 0.f};
; #pragma unroll
;                 for (int m = 0; m < 4; ++m) {
;                     const f32x4 g = acc[ai][1][m][n] * rs[ai][m], v = acc[ai][0][m][n] * rs[ai][m];
;                     f32x4 r1, r2, a;
; #pragma unroll
;                     for (int e = 0; e < 4; ++e) { r1[e] = __shfl(g[e], src1); r2[e] = __shfl(g[e], src2); }
; #pragma unroll
;                     for (int e = 0; e < 4; ++e) {
;                         const float p1 = fr >= 1 ? r1[e] : r1p[e], p2 = fr >= 2 ? r2[e] : r2p[e];
;                         const float gg = b4[e] + w0[e] * p2 + w1[e] * p1 + w2[e] * g[e];
;                         a[e] = gg * __builtin_amdgcn_rcpf(1.f + __expf(-gg)) * v[e];
;                     }
;                     r1p = r1; r2p = r2;
;                     const size_t row = (size_t)(u.pm * BM + ai * HALF + wr * 64 + m * 16 + fr);
;                     if (m == 0 && fr < 2) {
;                         *(f32x4*)(GF + (size_t)(slab * 2 + fr) * FF + cbase) = g; *(f32x4*)(VF + (size_t)(slab * 2 + fr) * FF + cbase) = v;
;                     } else {
;                         typedef unsigned u32x2v __attribute__((ext_vector_type(2)));
;                         u32x2v w; w.x = cvt_pk_bf16(a[0], a[1]); w.y = cvt_pk_bf16(a[2], a[3]);
;                         *(u32x2v*)(ACT + row * FF + cbase) = w;
;                     }
;                     if (m == 3 && fr >= 14) *(f32x4*)(GL + (size_t)(slab * 2 + fr - 14) * FF + cbase) = g;
.LBB0_53:
	s_or_b64 exec, exec, s[10:11]
	s_nop 0
	v_or_b32_e32 v70, 16, v156
	v_ashrrev_i32_e32 v71, 31, v70
	v_lshlrev_b64 v[70:71], 2, v[70:71]
	v_lshl_add_u64 v[72:73], s[60:61], 0, v[70:71]
	v_lshl_add_u64 v[70:71], s[62:63], 0, v[70:71]
	v_mov_b32_e32 v66, v208
	v_mov_b32_e32 v67, v209
	v_mov_b32_e32 v68, v210
	v_mov_b32_e32 v69, v211
	v_mov_b32_e32 v78, v212
	v_mov_b32_e32 v79, v213
	v_mov_b32_e32 v80, v214
	v_mov_b32_e32 v81, v215
	v_mov_b32_e32 v74, v216
	v_mov_b32_e32 v75, v217
	v_mov_b32_e32 v76, v218
	v_mov_b32_e32 v77, v219
	v_mov_b32_e32 v70, v220
	v_mov_b32_e32 v71, v221
	v_mov_b32_e32 v72, v222
	v_mov_b32_e32 v73, v223
	v_mov_b32_e32 v163, v162
	v_mov_b32_e32 v120, v162
	v_mov_b32_e32 v121, v162
	v_pk_mul_f32 v[84:85], v[60:61], v[120:121]
	v_pk_mul_f32 v[82:83], v[58:59], v[162:163]
	ds_bpermute_b32 v101, v161, v82
	ds_bpermute_b32 v91, v200, v82
	ds_bpermute_b32 v115, v161, v83
	ds_bpermute_b32 v93, v200, v83
	ds_bpermute_b32 v117, v161, v84
	ds_bpermute_b32 v95, v200, v84
	ds_bpermute_b32 v119, v161, v85
	ds_bpermute_b32 v103, v200, v85
	v_pk_mul_f32 v[60:61], v[64:65], v[120:121]
	v_pk_mul_f32 v[58:59], v[62:63], v[162:163]
	s_and_saveexec_b64 s[10:11], s[42:43]
	s_xor_b64 s[10:11], exec, s[10:11]
	s_cbranch_execz .LBB0_55
	v_mov_b32_e32 v62, v85
	s_nop 0
	v_mov_b32_e32 v63, v81
	s_nop 0
	v_mov_b32_e32 v118, v77
	s_waitcnt lgkmcnt(1)
	v_pk_mul_f32 v[62:63], v[62:63], v[118:119]
	s_waitcnt lgkmcnt(0)
	v_fma_f32 v64, v69, v103, v73
	v_add_f32_e32 v63, v63, v64
	v_add_f32_e32 v62, v62, v63
	v_mul_f32_e32 v63, 0xbfb8aa3b, v62
	v_exp_f32_e32 v63, v63
	v_mov_b32_e32 v85, v80
	v_mov_b32_e32 v116, v76
	v_mov_b32_e32 v114, v75
	v_add_f32_e32 v63, 1.0, v63
	v_rcp_f32_e32 v63, v63
	v_mov_b32_e32 v100, v74
	v_mul_f32_e32 v62, v62, v63
	v_mul_f32_e32 v64, v61, v62
	v_pk_mul_f32 v[62:63], v[84:85], v[116:117]
	v_fma_f32 v61, v68, v95, v72
	v_add_f32_e32 v61, v63, v61
	v_add_f32_e32 v61, v62, v61
	v_mul_f32_e32 v62, 0xbfb8aa3b, v61
	v_exp_f32_e32 v62, v62
	v_fma_f32 v63, v67, v93, v71
	v_add_f32_e32 v62, 1.0, v62
	v_rcp_f32_e32 v62, v62
	s_nop 0
	v_mul_f32_e32 v61, v61, v62
	v_mul_f32_e32 v62, v60, v61
	v_mov_b32_e32 v60, v83
	v_mov_b32_e32 v61, v79
	v_pk_mul_f32 v[60:61], v[60:61], v[114:115]
	v_mov_b32_e32 v83, v78
	v_add_f32_e32 v61, v61, v63
	v_add_f32_e32 v60, v60, v61
	v_mul_f32_e32 v61, 0xbfb8aa3b, v60
	v_exp_f32_e32 v61, v61
	v_fma_f32 v63, v66, v91, v70
	v_add_f32_e32 v61, 1.0, v61
	v_rcp_f32_e32 v61, v61
	s_nop 0
	v_mul_f32_e32 v60, v60, v61
	v_mul_f32_e32 v59, v59, v60
	v_pk_mul_f32 v[60:61], v[82:83], v[100:101]
	s_nop 0
	v_add_f32_e32 v61, v61, v63
	v_add_f32_e32 v60, v60, v61
	v_mul_f32_e32 v61, 0xbfb8aa3b, v60
	v_exp_f32_e32 v61, v61
	s_nop 0
	v_add_f32_e32 v61, 1.0, v61
	v_rcp_f32_e32 v61, v61
	s_nop 0
	v_mul_f32_e32 v60, v60, v61
	v_mul_f32_e32 v58, v58, v60
	v_mov_b64_e32 v[60:61], s[48:49]
	v_mad_i64_i32 v[60:61], s[12:13], v160, s17, v[60:61]
	v_cvt_pk_bf16_f32 v58, v58, v59
	v_cvt_pk_bf16_f32 v59, v62, v64
	v_lshl_add_u64 v[60:61], v[156:157], 1, v[60:61]
	v_mov_b32_e32 v64, v77
	v_mov_b32_e32 v62, v75
	global_store_dwordx2 v[60:61], v[58:59], off offset:32
.LBB0_55:
	s_andn2_saveexec_b64 s[10:11], s[10:11]
	s_cbranch_execz .LBB0_57
	v_lshl_add_u64 v[62:63], v[144:145], 0, v[158:159]
	global_store_dwordx4 v[62:63], v[82:85], off offset:64
	v_lshl_add_u64 v[62:63], v[168:169], 0, v[158:159]
	global_store_dwordx4 v[62:63], v[58:61], off offset:64
	s_nop 0
	v_mov_b32_e32 v62, v75
	v_mov_b32_e32 v64, v77
.LBB0_57:
	s_or_b64 exec, exec, s[10:11]
	v_mov_b32_e32 v58, v142
	v_mov_b32_e32 v59, v142
	v_pk_mul_f32 v[56:57], v[56:57], v[58:59]
	ds_bpermute_b32 v83, v161, v57
	ds_bpermute_b32 v114, v200, v57
	v_mov_b32_e32 v60, v57
	s_nop 0
	v_mov_b32_e32 v61, v81
	v_pk_mul_f32 v[52:53], v[52:53], v[58:59]
	s_waitcnt lgkmcnt(1)
	v_cndmask_b32_e64 v65, v83, v119, s[40:41]
	s_waitcnt lgkmcnt(0)
	v_cndmask_b32_e64 v57, v103, v114, s[42:43]
	v_pk_mul_f32 v[60:61], v[60:61], v[64:65]
	s_nop 0
	v_fma_f32 v57, v69, v57, v73
	v_add_f32_e32 v57, v61, v57
	v_add_f32_e32 v60, v60, v57
	v_mul_f32_e32 v57, 0xbfb8aa3b, v60
	v_exp_f32_e32 v57, v57
	ds_bpermute_b32 v61, v161, v56
	ds_bpermute_b32 v103, v200, v56
	v_mov_b32_e32 v143, v142
	v_add_f32_e32 v57, 1.0, v57
	v_rcp_f32_e32 v58, v57
	s_waitcnt lgkmcnt(1)
	v_cndmask_b32_e64 v77, v61, v117, s[40:41]
	v_mov_b32_e32 v57, v80
	s_waitcnt lgkmcnt(0)
	v_cndmask_b32_e64 v59, v95, v103, s[42:43]
	v_pk_mul_f32 v[56:57], v[56:57], v[76:77]
	v_fma_f32 v59, v68, v59, v72
	v_add_f32_e32 v57, v57, v59
	v_add_f32_e32 v59, v56, v57
	v_pk_mul_f32 v[54:55], v[54:55], v[142:143]
	v_mul_f32_e32 v56, 0xbfb8aa3b, v59
	ds_bpermute_b32 v85, v161, v55
	ds_bpermute_b32 v100, v200, v55
	v_exp_f32_e32 v56, v56
	v_mul_f32_e32 v57, v60, v58
	ds_bpermute_b32 v82, v161, v54
	ds_bpermute_b32 v84, v200, v54
	v_add_f32_e32 v56, 1.0, v56
	v_mul_f32_e32 v53, v53, v57
	v_rcp_f32_e32 v58, v56
	s_waitcnt lgkmcnt(3)
	v_cndmask_b32_e64 v63, v85, v115, s[40:41]
	v_mov_b32_e32 v56, v55
	v_mov_b32_e32 v57, v79
	s_waitcnt lgkmcnt(2)
	v_cndmask_b32_e64 v55, v93, v100, s[42:43]
	v_pk_mul_f32 v[56:57], v[56:57], v[62:63]
	v_fma_f32 v55, v67, v55, v71
	v_add_f32_e32 v55, v57, v55
	v_add_f32_e32 v56, v56, v55
	v_mul_f32_e32 v55, 0xbfb8aa3b, v56
	v_exp_f32_e32 v57, v55
	s_waitcnt lgkmcnt(1)
	v_cndmask_b32_e64 v75, v82, v101, s[40:41]
	v_mov_b32_e32 v55, v78
	s_waitcnt lgkmcnt(0)
; __device__ __forceinline__ unsigned cvt_pk_bf16(float lo, float hi) { unsigned r; asm volatile("v_cvt_pk_bf16_f32 %0, %1, %2" : "=v"(r) : "v"(lo), "v"(hi)); return r; }
;     __device__ __forceinline__ void operator()(const f32x4 (&acc)[2][2][4][2], const Unit& u, int wr, int wc, int fr, int fq) const {
;     ...
;                 for (int m = 0; m < 4; ++m) {
;                     const f32x4 g = acc[ai][1][m][n] * rs[ai][m], v = acc[ai][0][m][n] * rs[ai][m];
;                     f32x4 r1, r2, a;
; #pragma unroll
;                     for (int e = 0; e < 4; ++e) { r1[e] = __shfl(g[e], src1); r2[e] = __shfl(g[e], src2); }
; #pragma unroll
;                     for (int e = 0; e < 4; ++e) {
;                         const float p1 = fr >= 1 ? r1[e] : r1p[e], p2 = fr >= 2 ? r2[e] : r2p[e];
;                         const float gg = b4[e] + w0[e] * p2 + w1[e] * p1 + w2[e] * g[e];
;                         a[e] = gg * __builtin_amdgcn_rcpf(1.f + __expf(-gg)) * v[e];
;                     }
;                     r1p = r1; r2p = r2;
;                     const size_t row = (size_t)(u.pm * BM + ai * HALF + wr * 64 + m * 16 + fr);
;                     if (m == 0 && fr < 2) {
;                         *(f32x4*)(GF + (size_t)(slab * 2 + fr) * FF + cbase) = g; *(f32x4*)(VF + (size_t)(slab * 2 + fr) * FF + cbase) = v;
;                     } else {
;                         typedef unsigned u32x2v __attribute__((ext_vector_type(2)));
;                         u32x2v w; w.x = cvt_pk_bf16(a[0], a[1]); w.y = cvt_pk_bf16(a[2], a[3]);
;                         *(u32x2v*)(ACT + row * FF + cbase) = w;
;                     }
;                     if (m == 3 && fr >= 14) *(f32x4*)(GL + (size_t)(slab * 2 + fr - 14) * FF + cbase) = g;
	v_cndmask_b32_e64 v60, v91, v84, s[42:43]
	v_pk_mul_f32 v[54:55], v[54:55], v[74:75]
	v_fma_f32 v60, v66, v60, v70
	v_add_f32_e32 v55, v55, v60
	v_add_f32_e32 v54, v54, v55
	v_mul_f32_e32 v55, 0xbfb8aa3b, v54
	v_exp_f32_e32 v55, v55
	v_add_f32_e32 v57, 1.0, v57
	v_rcp_f32_e32 v57, v57
	v_pk_mul_f32 v[50:51], v[50:51], v[142:143]
	v_add_f32_e32 v55, 1.0, v55
	v_rcp_f32_e32 v55, v55
	v_mul_f32_e32 v56, v56, v57
	v_mul_f32_e32 v58, v59, v58
	v_mul_f32_e32 v51, v51, v56
	v_mul_f32_e32 v54, v54, v55
	v_mul_f32_e32 v50, v50, v54
	v_mul_f32_e32 v52, v52, v58
	v_cvt_pk_bf16_f32 v50, v50, v51
	v_cvt_pk_bf16_f32 v51, v52, v53
	global_store_dwordx2 v[122:123], v[50:51], off offset:32
	v_mov_b32_e32 v50, v136
	v_mov_b32_e32 v51, v136
	v_pk_mul_f32 v[48:49], v[48:49], v[50:51]
	ds_bpermute_b32 v55, v161, v49
	ds_bpermute_b32 v59, v200, v49
	v_mov_b32_e32 v52, v49
	v_mov_b32_e32 v53, v81
	ds_bpermute_b32 v60, v200, v48
	s_waitcnt lgkmcnt(2)
	v_cndmask_b32_e64 v65, v55, v83, s[40:41]
	s_waitcnt lgkmcnt(1)
	v_cndmask_b32_e64 v49, v114, v59, s[42:43]
	v_pk_mul_f32 v[52:53], v[52:53], v[64:65]
	v_fma_f32 v49, v69, v49, v73
	v_add_f32_e32 v49, v53, v49
	v_add_f32_e32 v52, v52, v49
	v_mul_f32_e32 v49, 0xbfb8aa3b, v52
	v_exp_f32_e32 v49, v49
	ds_bpermute_b32 v53, v161, v48
	v_pk_mul_f32 v[44:45], v[44:45], v[50:51]
	s_waitcnt lgkmcnt(1)
	v_cndmask_b32_e64 v51, v103, v60, s[42:43]
	v_add_f32_e32 v49, 1.0, v49
	v_rcp_f32_e32 v50, v49
	s_waitcnt lgkmcnt(0)
	v_cndmask_b32_e64 v77, v53, v61, s[40:41]
	v_mov_b32_e32 v49, v80
	v_pk_mul_f32 v[48:49], v[48:49], v[76:77]
	v_fma_f32 v51, v68, v51, v72
	v_add_f32_e32 v49, v49, v51
	v_mov_b32_e32 v137, v136
	v_add_f32_e32 v51, v48, v49
	v_pk_mul_f32 v[46:47], v[46:47], v[136:137]
	v_mul_f32_e32 v48, 0xbfb8aa3b, v51
	ds_bpermute_b32 v57, v161, v47
	ds_bpermute_b32 v58, v200, v47
	v_exp_f32_e32 v48, v48
	v_mul_f32_e32 v49, v52, v50
	ds_bpermute_b32 v54, v161, v46
	ds_bpermute_b32 v56, v200, v46
	v_add_f32_e32 v48, 1.0, v48
	v_mul_f32_e32 v45, v45, v49
	v_rcp_f32_e32 v50, v48
	s_waitcnt lgkmcnt(3)
	v_cndmask_b32_e64 v63, v57, v85, s[40:41]
	v_mov_b32_e32 v48, v47
	v_mov_b32_e32 v49, v79
	s_waitcnt lgkmcnt(2)
	v_cndmask_b32_e64 v47, v100, v58, s[42:43]
	v_pk_mul_f32 v[48:49], v[48:49], v[62:63]
	v_fma_f32 v47, v67, v47, v71
	v_add_f32_e32 v47, v49, v47
	v_add_f32_e32 v48, v48, v47
	v_mul_f32_e32 v47, 0xbfb8aa3b, v48
	v_exp_f32_e32 v49, v47
	s_waitcnt lgkmcnt(1)
	v_cndmask_b32_e64 v75, v54, v82, s[40:41]
	v_mov_b32_e32 v47, v78
	s_waitcnt lgkmcnt(0)
	v_cndmask_b32_e64 v52, v84, v56, s[42:43]
	v_pk_mul_f32 v[46:47], v[46:47], v[74:75]
	v_fma_f32 v52, v66, v52, v70
	v_add_f32_e32 v47, v47, v52
	v_add_f32_e32 v46, v46, v47
	v_mul_f32_e32 v47, 0xbfb8aa3b, v46
	v_exp_f32_e32 v47, v47
	v_add_f32_e32 v49, 1.0, v49
	v_rcp_f32_e32 v49, v49
	v_pk_mul_f32 v[42:43], v[42:43], v[136:137]
	v_add_f32_e32 v47, 1.0, v47
	v_rcp_f32_e32 v47, v47
	v_mul_f32_e32 v48, v48, v49
	v_mul_f32_e32 v50, v51, v50
	v_mul_f32_e32 v43, v43, v48
	v_mul_f32_e32 v46, v46, v47
	v_mul_f32_e32 v42, v42, v46
	v_mul_f32_e32 v44, v44, v50
	v_cvt_pk_bf16_f32 v42, v42, v43
	v_cvt_pk_bf16_f32 v43, v44, v45
	global_store_dwordx2 v[108:109], v[42:43], off offset:32
	v_mov_b32_e32 v42, v134
	v_mov_b32_e32 v43, v134
	v_pk_mul_f32 v[40:41], v[40:41], v[42:43]
	ds_bpermute_b32 v44, v161, v41
	ds_bpermute_b32 v50, v200, v41
	v_mov_b32_e32 v45, v81
	ds_bpermute_b32 v51, v200, v40
	v_pk_mul_f32 v[36:37], v[36:37], v[42:43]
	s_waitcnt lgkmcnt(2)
	v_cndmask_b32_e64 v65, v44, v55, s[40:41]
	v_mov_b32_e32 v44, v41
	s_waitcnt lgkmcnt(1)
	v_cndmask_b32_e64 v50, v59, v50, s[42:43]
	v_pk_mul_f32 v[44:45], v[44:45], v[64:65]
	v_fma_f32 v50, v69, v50, v73
	v_add_f32_e32 v45, v45, v50
	v_add_f32_e32 v44, v44, v45
	v_mul_f32_e32 v45, 0xbfb8aa3b, v44
	v_exp_f32_e32 v45, v45
	ds_bpermute_b32 v50, v161, v40
	v_mov_b32_e32 v43, v80
	v_mov_b32_e32 v135, v134
	v_add_f32_e32 v42, 1.0, v45
	v_rcp_f32_e32 v45, v42
	s_waitcnt lgkmcnt(0)
	v_cndmask_b32_e64 v77, v50, v53, s[40:41]
	v_mov_b32_e32 v42, v40
	v_cndmask_b32_e64 v50, v60, v51, s[42:43]
	v_pk_mul_f32 v[42:43], v[42:43], v[76:77]
	v_fma_f32 v50, v68, v50, v72
	v_add_f32_e32 v43, v43, v50
	v_add_f32_e32 v50, v42, v43
	v_pk_mul_f32 v[38:39], v[38:39], v[134:135]
	v_mul_f32_e32 v42, 0xbfb8aa3b, v50
	ds_bpermute_b32 v48, v161, v39
	ds_bpermute_b32 v49, v200, v39
	v_exp_f32_e32 v42, v42
	v_mul_f32_e32 v43, v44, v45
	ds_bpermute_b32 v46, v161, v38
	ds_bpermute_b32 v47, v200, v38
	v_add_f32_e32 v42, 1.0, v42
	v_mul_f32_e32 v37, v37, v43
	v_rcp_f32_e32 v44, v42
	s_waitcnt lgkmcnt(3)
	v_cndmask_b32_e64 v63, v48, v57, s[40:41]
	v_mov_b32_e32 v42, v39
	v_mov_b32_e32 v43, v79
	s_waitcnt lgkmcnt(2)
	v_cndmask_b32_e64 v45, v58, v49, s[42:43]
	v_pk_mul_f32 v[42:43], v[42:43], v[62:63]
	v_fma_f32 v45, v67, v45, v71
	v_add_f32_e32 v43, v43, v45
	v_add_f32_e32 v45, v42, v43
	v_mul_f32_e32 v42, 0xbfb8aa3b, v45
	v_exp_f32_e32 v48, v42
	s_waitcnt lgkmcnt(1)
	v_cndmask_b32_e64 v75, v46, v54, s[40:41]
	v_mov_b32_e32 v42, v38
	v_mov_b32_e32 v43, v78
	s_waitcnt lgkmcnt(0)
	v_cndmask_b32_e64 v46, v56, v47, s[42:43]
	v_pk_mul_f32 v[42:43], v[42:43], v[74:75]
	v_fma_f32 v46, v66, v46, v70
	v_add_f32_e32 v43, v43, v46
	v_add_f32_e32 v42, v42, v43
	v_mul_f32_e32 v43, 0xbfb8aa3b, v42
	v_exp_f32_e32 v43, v43
	v_add_f32_e32 v46, 1.0, v48
	v_rcp_f32_e32 v46, v46
	v_mul_f32_e32 v44, v50, v44
	v_add_f32_e32 v43, 1.0, v43
	v_rcp_f32_e32 v43, v43
	v_pk_mul_f32 v[34:35], v[34:35], v[134:135]
	v_mul_f32_e32 v36, v36, v44
	v_mul_f32_e32 v44, v45, v46
	v_mul_f32_e32 v42, v42, v43
	v_mul_f32_e32 v35, v35, v44
	v_mul_f32_e32 v34, v34, v42
	v_cvt_pk_bf16_f32 v34, v34, v35
	v_cvt_pk_bf16_f32 v35, v36, v37
	global_store_dwordx2 v[110:111], v[34:35], off offset:32
	s_and_saveexec_b64 s[10:11], s[44:45]
	s_cbranch_execz .LBB0_59
	global_store_dwordx4 v[106:107], v[38:41], off offset:64

; __device__ __forceinline__ unsigned cvt_pk_bf16(float lo, float hi) { unsigned r; asm volatile("v_cvt_pk_bf16_f32 %0, %1, %2" : "=v"(r) : "v"(lo), "v"(hi)); return r; }
;     __device__ __forceinline__ void operator()(const f32x4 (&acc)[2][2][4][2], const Unit& u, int wr, int wc, int fr, int fq) const {
;         const int row0 = u.pm * BM + wr * 64 + fr; const bool second = split > 0 && u.pn >= split; const int col0 = (second ? u.pn - split : u.pn) * BM + wc * 32 + 8 * fq;
;         bf16_t* const Ob = second ? O2 : O; const int ld = second ? ldc2 : ldc;
; #pragma unroll
;         for (int ai = 0; ai < 2; ++ai)
; #pragma unroll
;             for (int m = 0; m < 4; ++m) { bf16_t* rowp = Ob + (size_t)(row0 + ai * HALF + m * 16) * ld + col0;
;                 float rs = 1.f; if (ss) rs = __builtin_amdgcn_rsqf((float)ss[row0 + ai * HALF + m * 16] * (1.f / (2048.f * 262144.f)) + 1e-6f);
; #pragma unroll
;                 for (int bj = 0; bj < 2; ++bj) { const f32x4 v0 = acc[ai][bj][m][0] * rs, v1 = acc[ai][bj][m][1] * rs;
;                     u32x4 w; w.x = cvt_pk_bf16(v0[0], v0[1]); w.y = cvt_pk_bf16(v0[2], v0[3]); w.z = cvt_pk_bf16(v1[0], v1[1]); w.w = cvt_pk_bf16(v1[2], v1[3]);
;                     *(u32x4*)(rowp + bj * HALF) = w; } }
.LBB0_172:
	v_lshl_add_u32 v144, s42, 8, v149
	v_ashrrev_i32_e32 v145, 31, v144
	v_cndmask_b32_e64 v140, 0, 1, s[36:37]
	v_mov_b32_e32 v148, 1.0
	v_cmp_ne_u32_e64 s[42:43], 1, v140
	s_andn2_b64 vcc, exec, s[36:37]
	v_lshl_add_u64 v[142:143], v[144:145], 3, s[14:15]
	v_mov_b32_e32 v150, 1.0
	s_cbranch_vccnz .LBB0_174
	global_load_dwordx2 v[160:161], v[142:143], off
	global_load_dwordx2 v[162:163], v[142:143], off offset:128
	global_load_dwordx2 v[164:165], v[142:143], off offset:256
	global_load_dwordx2 v[166:167], v[142:143], off offset:384
	global_load_dwordx2 v[168:169], v[142:143], off offset:1024
	global_load_dwordx2 v[170:171], v[142:143], off offset:1152
	global_load_dwordx2 v[172:173], v[142:143], off offset:1280
	global_load_dwordx2 v[174:175], v[142:143], off offset:1408
	s_waitcnt vmcnt(7)
	v_mov_b32_e32 v140, v160
	v_mov_b32_e32 v141, v161
	v_ffbh_u32_e32 v146, v141
	v_min_u32_e32 v146, 32, v146
	v_lshlrev_b64 v[140:141], v146, v[140:141]
	v_min_u32_e32 v140, 1, v140
	v_or_b32_e32 v140, v141, v140
	v_cvt_f32_u32_e32 v140, v140
	v_sub_u32_e32 v141, 32, v146
	v_ldexp_f32 v140, v140, v141
	v_fmamk_f32 v140, v140, 0x31000000, v232
	v_rsq_f32_e32 v150, v140
.LBB0_174:
	v_lshl_or_b32 v140, s54, 8, v152
	v_ashrrev_i32_e32 v141, 31, v140
	v_lshl_add_u64 v[146:147], v[140:141], 1, s[48:49]
	v_lshlrev_b64 v[140:141], 10, v[144:145]
	v_lshl_add_u64 v[140:141], v[146:147], 0, v[140:141]
	v_pk_mul_f32 v[128:129], v[128:129], v[150:151] op_sel_hi:[1,0]
	v_pk_mul_f32 v[126:127], v[126:127], v[150:151] op_sel_hi:[1,0]
	v_pk_mul_f32 v[154:155], v[124:125], v[150:151] op_sel_hi:[1,0]
	v_pk_mul_f32 v[124:125], v[122:123], v[150:151] op_sel_hi:[1,0]
	v_cvt_pk_bf16_f32 v122, v126, v127
	v_cvt_pk_bf16_f32 v123, v128, v129
	s_and_b64 vcc, exec, s[42:43]
	v_cvt_pk_bf16_f32 v124, v124, v125
	v_cvt_pk_bf16_f32 v125, v154, v155
	global_store_dwordx4 v[140:141], v[122:125], off
	v_pk_mul_f32 v[120:121], v[120:121], v[150:151] op_sel_hi:[1,0]
	v_pk_mul_f32 v[118:119], v[118:119], v[150:151] op_sel_hi:[1,0]
	v_pk_mul_f32 v[122:123], v[116:117], v[150:151] op_sel_hi:[1,0]
	v_pk_mul_f32 v[116:117], v[114:115], v[150:151] op_sel_hi:[1,0]
	v_cvt_pk_bf16_f32 v114, v118, v119
	v_cvt_pk_bf16_f32 v115, v120, v121
	s_nop 0
	v_cvt_pk_bf16_f32 v116, v116, v117
	v_cvt_pk_bf16_f32 v117, v122, v123
	global_store_dwordx4 v[140:141], v[114:117], off offset:256
	s_cbranch_vccnz .LBB0_176
	s_waitcnt vmcnt(8)
	v_mov_b32_e32 v114, v162
	v_mov_b32_e32 v115, v163
	v_ffbh_u32_e32 v116, v115
	v_min_u32_e32 v116, 32, v116
	v_lshlrev_b64 v[114:115], v116, v[114:115]
	v_min_u32_e32 v114, 1, v114
	v_or_b32_e32 v114, v115, v114
	v_cvt_f32_u32_e32 v114, v114
	v_sub_u32_e32 v115, 32, v116
	v_ldexp_f32 v114, v114, v115
	v_fmamk_f32 v114, v114, 0x31000000, v232
	v_rsq_f32_e32 v148, v114
.LBB0_176:
	s_nop 0
	v_or_b32_e32 v114, 16, v144
	v_ashrrev_i32_e32 v115, 31, v114
	v_lshlrev_b64 v[114:115], 10, v[114:115]
	v_lshl_add_u64 v[114:115], v[146:147], 0, v[114:115]
	v_pk_mul_f32 v[112:113], v[112:113], v[148:149] op_sel_hi:[1,0]
	v_pk_mul_f32 v[110:111], v[110:111], v[148:149] op_sel_hi:[1,0]
	v_pk_mul_f32 v[116:117], v[108:109], v[148:149] op_sel_hi:[1,0]
	v_pk_mul_f32 v[108:109], v[106:107], v[148:149] op_sel_hi:[1,0]
	v_cvt_pk_bf16_f32 v106, v110, v111
	v_cvt_pk_bf16_f32 v107, v112, v113
	v_pk_mul_f32 v[104:105], v[104:105], v[148:149] op_sel_hi:[1,0]
	v_cvt_pk_bf16_f32 v108, v108, v109
	v_cvt_pk_bf16_f32 v109, v116, v117
	global_store_dwordx4 v[114:115], v[106:109], off
	v_pk_mul_f32 v[102:103], v[102:103], v[148:149] op_sel_hi:[1,0]
	s_and_b64 vcc, exec, s[42:43]
	v_pk_mul_f32 v[106:107], v[100:101], v[148:149] op_sel_hi:[1,0]
	v_pk_mul_f32 v[100:101], v[98:99], v[148:149] op_sel_hi:[1,0]
	v_cvt_pk_bf16_f32 v98, v102, v103
	v_cvt_pk_bf16_f32 v99, v104, v105
	s_nop 0
	v_cvt_pk_bf16_f32 v100, v100, v101
	v_cvt_pk_bf16_f32 v101, v106, v107
	global_store_dwordx4 v[114:115], v[98:101], off offset:256
	s_nop 1
	v_mov_b32_e32 v98, 1.0
	v_mov_b32_e32 v100, 1.0
	s_cbranch_vccnz .LBB0_178
	s_waitcnt vmcnt(9)
	v_mov_b32_e32 v100, v164
	v_mov_b32_e32 v101, v165
	v_ffbh_u32_e32 v99, v101
	v_min_u32_e32 v99, 32, v99
	v_lshlrev_b64 v[100:101], v99, v[100:101]
	v_min_u32_e32 v100, 1, v100
	v_or_b32_e32 v100, v101, v100
	v_cvt_f32_u32_e32 v100, v100
	v_sub_u32_e32 v99, 32, v99
	v_ldexp_f32 v99, v100, v99
	v_fmamk_f32 v99, v99, 0x31000000, v232
	v_rsq_f32_e32 v100, v99
.LBB0_178:
	v_or_b32_e32 v102, 32, v144
	v_ashrrev_i32_e32 v103, 31, v102
	v_lshlrev_b64 v[102:103], 10, v[102:103]
	v_lshl_add_u64 v[102:103], v[146:147], 0, v[102:103]
	v_pk_mul_f32 v[96:97], v[96:97], v[100:101] op_sel_hi:[1,0]
	v_pk_mul_f32 v[94:95], v[94:95], v[100:101] op_sel_hi:[1,0]
	v_pk_mul_f32 v[104:105], v[92:93], v[100:101] op_sel_hi:[1,0]
	v_pk_mul_f32 v[92:93], v[90:91], v[100:101] op_sel_hi:[1,0]
	v_cvt_pk_bf16_f32 v90, v94, v95
	v_cvt_pk_bf16_f32 v91, v96, v97
	s_and_b64 vcc, exec, s[42:43]
	v_cvt_pk_bf16_f32 v92, v92, v93
	v_cvt_pk_bf16_f32 v93, v104, v105
	global_store_dwordx4 v[102:103], v[90:93], off
	v_pk_mul_f32 v[88:89], v[88:89], v[100:101] op_sel_hi:[1,0]
	v_pk_mul_f32 v[86:87], v[86:87], v[100:101] op_sel_hi:[1,0]
	v_pk_mul_f32 v[90:91], v[84:85], v[100:101] op_sel_hi:[1,0]
	v_pk_mul_f32 v[84:85], v[82:83], v[100:101] op_sel_hi:[1,0]
	v_cvt_pk_bf16_f32 v82, v86, v87
	v_cvt_pk_bf16_f32 v83, v88, v89
	s_nop 0
	v_cvt_pk_bf16_f32 v84, v84, v85
	v_cvt_pk_bf16_f32 v85, v90, v91
	global_store_dwordx4 v[102:103], v[82:85], off offset:256
	s_cbranch_vccnz .LBB0_180
	s_waitcnt vmcnt(10)
	v_mov_b32_e32 v82, v166
	v_mov_b32_e32 v83, v167
	v_ffbh_u32_e32 v84, v83
	v_min_u32_e32 v84, 32, v84
	v_lshlrev_b64 v[82:83], v84, v[82:83]
	v_min_u32_e32 v82, 1, v82
	v_or_b32_e32 v82, v83, v82
	v_cvt_f32_u32_e32 v82, v82
	v_sub_u32_e32 v83, 32, v84
	v_ldexp_f32 v82, v82, v83
	v_fmamk_f32 v82, v82, 0x31000000, v232
	v_rsq_f32_e32 v98, v82
; __device__ __forceinline__ unsigned cvt_pk_bf16(float lo, float hi) { unsigned r; asm volatile("v_cvt_pk_bf16_f32 %0, %1, %2" : "=v"(r) : "v"(lo), "v"(hi)); return r; }
;     __device__ __forceinline__ void operator()(const f32x4 (&acc)[2][2][4][2], const Unit& u, int wr, int wc, int fr, int fq) const {
;     ...
;             for (int m = 0; m < 4; ++m) { bf16_t* rowp = Ob + (size_t)(row0 + ai * HALF + m * 16) * ld + col0;
;                 float rs = 1.f; if (ss) rs = __builtin_amdgcn_rsqf((float)ss[row0 + ai * HALF + m * 16] * (1.f / (2048.f * 262144.f)) + 1e-6f);
; #pragma unroll
;                 for (int bj = 0; bj < 2; ++bj) { const f32x4 v0 = acc[ai][bj][m][0] * rs, v1 = acc[ai][bj][m][1] * rs;
;                     u32x4 w; w.x = cvt_pk_bf16(v0[0], v0[1]); w.y = cvt_pk_bf16(v0[2], v0[3]); w.z = cvt_pk_bf16(v1[0], v1[1]); w.w = cvt_pk_bf16(v1[2], v1[3]);
;                     *(u32x4*)(rowp + bj * HALF) = w; } }
.LBB0_180:
	s_nop 0
	v_or_b32_e32 v82, 48, v144
	v_ashrrev_i32_e32 v83, 31, v82
	v_lshlrev_b64 v[82:83], 10, v[82:83]
	v_lshl_add_u64 v[82:83], v[146:147], 0, v[82:83]
	v_pk_mul_f32 v[80:81], v[80:81], v[98:99] op_sel_hi:[1,0]
	v_pk_mul_f32 v[78:79], v[78:79], v[98:99] op_sel_hi:[1,0]
	v_pk_mul_f32 v[84:85], v[76:77], v[98:99] op_sel_hi:[1,0]
	v_pk_mul_f32 v[76:77], v[74:75], v[98:99] op_sel_hi:[1,0]
	v_cvt_pk_bf16_f32 v74, v78, v79
	v_cvt_pk_bf16_f32 v75, v80, v81
	v_pk_mul_f32 v[72:73], v[72:73], v[98:99] op_sel_hi:[1,0]
	v_cvt_pk_bf16_f32 v76, v76, v77
	v_cvt_pk_bf16_f32 v77, v84, v85
	global_store_dwordx4 v[82:83], v[74:77], off
	v_pk_mul_f32 v[70:71], v[70:71], v[98:99] op_sel_hi:[1,0]
	s_and_b64 vcc, exec, s[42:43]
	v_pk_mul_f32 v[74:75], v[68:69], v[98:99] op_sel_hi:[1,0]
	v_pk_mul_f32 v[68:69], v[66:67], v[98:99] op_sel_hi:[1,0]
	v_cvt_pk_bf16_f32 v66, v70, v71
	v_cvt_pk_bf16_f32 v67, v72, v73
	s_nop 0
	v_cvt_pk_bf16_f32 v68, v68, v69
	v_cvt_pk_bf16_f32 v69, v74, v75
	global_store_dwordx4 v[82:83], v[66:69], off offset:256
	s_nop 1
	v_mov_b32_e32 v66, 1.0
	v_mov_b32_e32 v68, 1.0
	s_cbranch_vccnz .LBB0_182
	s_waitcnt vmcnt(11)
	v_mov_b32_e32 v68, v168
	v_mov_b32_e32 v69, v169
	v_ffbh_u32_e32 v67, v69
	v_min_u32_e32 v67, 32, v67
	v_lshlrev_b64 v[68:69], v67, v[68:69]
	v_min_u32_e32 v68, 1, v68
	v_or_b32_e32 v68, v69, v68
	v_cvt_f32_u32_e32 v68, v68
	v_sub_u32_e32 v67, 32, v67
	v_ldexp_f32 v67, v68, v67
	v_fmamk_f32 v67, v67, 0x31000000, v232
	v_rsq_f32_e32 v68, v67
.LBB0_182:
	s_nop 0
	v_pk_mul_f32 v[62:63], v[62:63], v[68:69] op_sel_hi:[1,0]
	s_mov_b32 s10, 0x20000
	v_pk_mul_f32 v[72:73], v[60:61], v[68:69] op_sel_hi:[1,0]
	v_pk_mul_f32 v[60:61], v[58:59], v[68:69] op_sel_hi:[1,0]
	v_cvt_pk_bf16_f32 v58, v62, v63
	v_add_co_u32_e32 v62, vcc, s10, v140
	v_pk_mul_f32 v[64:65], v[64:65], v[68:69] op_sel_hi:[1,0]
	s_nop 0
	v_addc_co_u32_e32 v63, vcc, 0, v141, vcc
	v_cvt_pk_bf16_f32 v59, v64, v65
	v_lshl_add_u64 v[70:71], v[140:141], 0, s[66:67]
	v_cvt_pk_bf16_f32 v60, v60, v61
	v_cvt_pk_bf16_f32 v61, v72, v73
	global_store_dwordx4 v[62:63], v[58:61], off
	s_and_b64 vcc, exec, s[42:43]
	v_pk_mul_f32 v[56:57], v[56:57], v[68:69] op_sel_hi:[1,0]
	v_pk_mul_f32 v[58:59], v[52:53], v[68:69] op_sel_hi:[1,0]
	v_pk_mul_f32 v[52:53], v[50:51], v[68:69] op_sel_hi:[1,0]
	v_pk_mul_f32 v[54:55], v[54:55], v[68:69] op_sel_hi:[1,0]
	s_nop 0
	v_cvt_pk_bf16_f32 v50, v54, v55
	v_cvt_pk_bf16_f32 v51, v56, v57
	v_cvt_pk_bf16_f32 v52, v52, v53
	v_cvt_pk_bf16_f32 v53, v58, v59
	global_store_dwordx4 v[70:71], v[50:53], off offset:256
	s_cbranch_vccnz .LBB0_184
	s_waitcnt vmcnt(12)
	v_mov_b32_e32 v50, v170
	v_mov_b32_e32 v51, v171
	v_ffbh_u32_e32 v52, v51
	v_min_u32_e32 v52, 32, v52
	v_lshlrev_b64 v[50:51], v52, v[50:51]
	v_min_u32_e32 v50, 1, v50
	v_or_b32_e32 v50, v51, v50
	v_cvt_f32_u32_e32 v50, v50
	v_sub_u32_e32 v51, 32, v52
	v_ldexp_f32 v50, v50, v51
	v_fmamk_f32 v50, v50, 0x31000000, v232
	v_rsq_f32_e32 v66, v50
.LBB0_184:
	s_nop 0
	v_pk_mul_f32 v[46:47], v[46:47], v[66:67] op_sel_hi:[1,0]
	v_pk_mul_f32 v[52:53], v[44:45], v[66:67] op_sel_hi:[1,0]
	v_pk_mul_f32 v[44:45], v[42:43], v[66:67] op_sel_hi:[1,0]
	v_cvt_pk_bf16_f32 v42, v46, v47
	v_add_co_u32_e32 v46, vcc, s86, v140
	v_pk_mul_f32 v[48:49], v[48:49], v[66:67] op_sel_hi:[1,0]
	s_nop 0
	v_addc_co_u32_e32 v47, vcc, 0, v141, vcc
	v_cvt_pk_bf16_f32 v43, v48, v49
	s_mov_b64 s[10:11], 0x24000
	v_cvt_pk_bf16_f32 v44, v44, v45
	v_cvt_pk_bf16_f32 v45, v52, v53
	global_store_dwordx4 v[46:47], v[42:45], off
	v_lshl_add_u64 v[50:51], v[140:141], 0, s[10:11]
	v_pk_mul_f32 v[40:41], v[40:41], v[66:67] op_sel_hi:[1,0]
	v_pk_mul_f32 v[42:43], v[36:37], v[66:67] op_sel_hi:[1,0]
	v_pk_mul_f32 v[36:37], v[34:35], v[66:67] op_sel_hi:[1,0]
	v_pk_mul_f32 v[38:39], v[38:39], v[66:67] op_sel_hi:[1,0]
	s_and_b64 vcc, exec, s[42:43]
	v_cvt_pk_bf16_f32 v34, v38, v39
	v_cvt_pk_bf16_f32 v35, v40, v41
	v_cvt_pk_bf16_f32 v36, v36, v37
	v_cvt_pk_bf16_f32 v37, v42, v43
	global_store_dwordx4 v[50:51], v[34:37], off offset:256
	s_nop 1
	v_mov_b32_e32 v34, 1.0
	v_mov_b32_e32 v36, 1.0
	s_cbranch_vccnz .LBB0_186
	s_waitcnt vmcnt(13)
	v_mov_b32_e32 v36, v172
	v_mov_b32_e32 v37, v173
	v_ffbh_u32_e32 v35, v37
	v_min_u32_e32 v35, 32, v35
	v_lshlrev_b64 v[36:37], v35, v[36:37]
	v_min_u32_e32 v36, 1, v36
	v_or_b32_e32 v36, v37, v36
	v_cvt_f32_u32_e32 v36, v36
	v_sub_u32_e32 v35, 32, v35
	v_ldexp_f32 v35, v36, v35
	v_fmamk_f32 v35, v35, 0x31000000, v232
	v_rsq_f32_e32 v36, v35
.LBB0_186:
	s_nop 0
	v_pk_mul_f32 v[30:31], v[30:31], v[36:37] op_sel_hi:[1,0]
	v_pk_mul_f32 v[40:41], v[28:29], v[36:37] op_sel_hi:[1,0]
	v_pk_mul_f32 v[28:29], v[26:27], v[36:37] op_sel_hi:[1,0]
	v_cvt_pk_bf16_f32 v26, v30, v31
	v_add_co_u32_e32 v30, vcc, s65, v140
	s_mov_b64 s[10:11], 0x28000
	v_pk_mul_f32 v[32:33], v[32:33], v[36:37] op_sel_hi:[1,0]
	v_addc_co_u32_e32 v31, vcc, 0, v141, vcc
	v_cvt_pk_bf16_f32 v27, v32, v33
	v_lshl_add_u64 v[38:39], v[140:141], 0, s[10:11]
	v_cvt_pk_bf16_f32 v28, v28, v29
	v_cvt_pk_bf16_f32 v29, v40, v41
	global_store_dwordx4 v[30:31], v[26:29], off
	s_and_b64 vcc, exec, s[42:43]
	v_pk_mul_f32 v[24:25], v[24:25], v[36:37] op_sel_hi:[1,0]
	v_pk_mul_f32 v[26:27], v[20:21], v[36:37] op_sel_hi:[1,0]
	v_pk_mul_f32 v[20:21], v[18:19], v[36:37] op_sel_hi:[1,0]
	v_pk_mul_f32 v[22:23], v[22:23], v[36:37] op_sel_hi:[1,0]
	s_nop 0
	v_cvt_pk_bf16_f32 v18, v22, v23
	v_cvt_pk_bf16_f32 v19, v24, v25
	v_cvt_pk_bf16_f32 v20, v20, v21
	v_cvt_pk_bf16_f32 v21, v26, v27
	global_store_dwordx4 v[38:39], v[18:21], off offset:256
	s_cbranch_vccnz .LBB0_188
	s_waitcnt vmcnt(14)
	v_mov_b32_e32 v18, v174
	v_mov_b32_e32 v19, v175
	v_ffbh_u32_e32 v20, v19
	v_min_u32_e32 v20, 32, v20
	v_lshlrev_b64 v[18:19], v20, v[18:19]
	v_min_u32_e32 v18, 1, v18
	v_or_b32_e32 v18, v19, v18
	v_cvt_f32_u32_e32 v18, v18
	v_sub_u32_e32 v19, 32, v20
	v_ldexp_f32 v18, v18, v19
	v_fmamk_f32 v18, v18, 0x31000000, v232
	v_rsq_f32_e32 v34, v18

; __device__ __forceinline__ unsigned cvt_pk_bf16(float lo, float hi) { unsigned r; asm volatile("v_cvt_pk_bf16_f32 %0, %1, %2" : "=v"(r) : "v"(lo), "v"(hi)); return r; }
;     __device__ __forceinline__ void operator()(const f32x4 (&acc)[2][2][4][2], const Unit& u, int wr, int wc, int fr, int fq) const {
;         const int col0 = u.pn * BM + wc * 32 + 8 * fq;
; #pragma unroll
;         for (int ai = 0; ai < 2; ++ai)
; #pragma unroll
;             for (int m = 0; m < 4; ++m) { const int row = u.pm * BM + ai * HALF + wr * 64 + m * 16 + fr; bf16_t* xp = x + (size_t)row * ldc + col0;
;                 u32x4 bv[2];
; #pragma unroll
;                 for (int bj = 0; bj < 2; ++bj) bv[bj] = *(const u32x4*)(xp + bj * HALF);
;                 float sq = 0.f;
; #pragma unroll
;                 for (int bj = 0; bj < 2; ++bj) { u32x4 w;
; #pragma unroll
;                     for (int n = 0; n < 2; ++n) { const f32x4 a = acc[ai][bj][m][n]; const unsigned b0 = bv[bj][2 * n], b1 = bv[bj][2 * n + 1];
;                         const float o0 = __builtin_bit_cast(float, b0 << 16) + a[0], o1 = __builtin_bit_cast(float, b0 & 0xffff0000u) + a[1];
;                         const float o2 = __builtin_bit_cast(float, b1 << 16) + a[2], o3 = __builtin_bit_cast(float, b1 & 0xffff0000u) + a[3];
;                         sq += (o0 * o0 + o1 * o1) + (o2 * o2 + o3 * o3);
;                         w[2 * n] = cvt_pk_bf16(o0, o1); w[2 * n + 1] = cvt_pk_bf16(o2, o3); }
;                     *(u32x4*)(xp + bj * HALF) = w; }
;                 if (ss) { sq += __shfl_xor(sq, 16); sq += __shfl_xor(sq, 32); if (fq == 0) __hip_atomic_fetch_add(ss + row, (unsigned long long)(sq * 262144.f + 0.5f), __ATOMIC_RELAXED, __HIP_MEMORY_SCOPE_AGENT); } }
.LBB0_226:
	v_lshl_add_u32 v140, s62, 8, v144
	v_ashrrev_i32_e32 v141, 31, v140
	v_lshl_or_b32 v142, s63, 8, v146
	v_lshlrev_b64 v[148:149], 12, v[140:141]
	v_ashrrev_i32_e32 v143, 31, v142
	v_lshl_add_u64 v[148:149], s[18:19], 0, v[148:149]
	v_lshl_add_u64 v[160:161], v[142:143], 1, v[148:149]
	global_load_dwordx4 v[162:165], v[160:161], off
	global_load_dwordx4 v[166:169], v[160:161], off offset:256
	v_add_co_u32_e32 v154, vcc, 0x10000, v160
	s_nop 1
	v_addc_co_u32_e32 v155, vcc, 0, v161, vcc
	global_load_dwordx4 v[170:173], v[154:155], off
	global_load_dwordx4 v[174:177], v[154:155], off offset:256
	v_add_co_u32_e32 v154, vcc, 0x20000, v160
	s_nop 1
	v_addc_co_u32_e32 v155, vcc, 0, v161, vcc
	global_load_dwordx4 v[178:181], v[154:155], off
	global_load_dwordx4 v[182:185], v[154:155], off offset:256
	v_add_co_u32_e32 v154, vcc, 0x30000, v160
	s_nop 1
	v_addc_co_u32_e32 v155, vcc, 0, v161, vcc
	global_load_dwordx4 v[186:189], v[154:155], off
	global_load_dwordx4 v[190:193], v[154:155], off offset:256
	v_add_co_u32_e32 v154, vcc, 0x80000, v160
	s_nop 1
	v_addc_co_u32_e32 v155, vcc, 0, v161, vcc
	global_load_dwordx4 v[194:197], v[154:155], off
	global_load_dwordx4 v[198:201], v[154:155], off offset:256
	v_add_co_u32_e32 v202, vcc, 0x90000, v160
	s_nop 1
	v_addc_co_u32_e32 v203, vcc, 0, v161, vcc
	v_add_co_u32_e32 v204, vcc, 0xa0000, v160
	s_nop 1
	v_addc_co_u32_e32 v205, vcc, 0, v161, vcc
	v_add_co_u32_e32 v206, vcc, 0xb0000, v160
	s_nop 1
	v_addc_co_u32_e32 v207, vcc, 0, v161, vcc
	s_andn2_b64 vcc, exec, s[48:49]
	s_waitcnt vmcnt(8)
	v_mov_b32_e32 v148, v162
	v_mov_b32_e32 v149, v163
	v_mov_b32_e32 v150, v164
	v_mov_b32_e32 v151, v165
	v_mov_b32_e32 v152, v166
	v_mov_b32_e32 v153, v167
	v_mov_b32_e32 v154, v168
	v_mov_b32_e32 v155, v169
	global_load_dwordx4 v[162:165], v[202:203], off
	global_load_dwordx4 v[166:169], v[202:203], off offset:256
	v_lshlrev_b32_e32 v156, 16, v148
	v_and_b32_e32 v148, 0xffff0000, v148
	v_add_f32_e32 v148, v127, v148
	v_lshlrev_b32_e32 v127, 16, v149
	v_add_f32_e32 v127, v128, v127
	v_and_b32_e32 v128, 0xffff0000, v149
	v_add_f32_e32 v128, v129, v128
	v_lshlrev_b32_e32 v129, 16, v150
	v_add_f32_e32 v122, v122, v129
	v_and_b32_e32 v129, 0xffff0000, v150
	v_add_f32_e32 v129, v123, v129
	v_lshlrev_b32_e32 v123, 16, v151
	v_add_f32_e32 v123, v124, v123
	v_and_b32_e32 v124, 0xffff0000, v151
	v_add_f32_e32 v124, v125, v124
	v_lshlrev_b32_e32 v125, 16, v152
	v_add_f32_e32 v118, v118, v125
	v_and_b32_e32 v125, 0xffff0000, v152
	v_add_f32_e32 v125, v119, v125
	v_lshlrev_b32_e32 v119, 16, v153
	v_add_f32_e32 v119, v120, v119
	v_and_b32_e32 v120, 0xffff0000, v153
	v_add_f32_e32 v120, v121, v120
	v_lshlrev_b32_e32 v121, 16, v154
	v_add_f32_e32 v114, v114, v121
	v_and_b32_e32 v121, 0xffff0000, v154
	v_add_f32_e32 v121, v115, v121
	v_lshlrev_b32_e32 v115, 16, v155
	v_add_f32_e32 v115, v116, v115
	v_and_b32_e32 v116, 0xffff0000, v155
	v_add_f32_e32 v116, v117, v116
	v_cndmask_b32_e64 v117, 0, 1, s[48:49]
	v_add_f32_e32 v126, v126, v156
	v_cmp_ne_u32_e64 s[44:45], 1, v117
	v_cvt_pk_bf16_f32 v156, v126, v148
	v_cvt_pk_bf16_f32 v157, v127, v128
	v_cvt_pk_bf16_f32 v158, v122, v129
	v_cvt_pk_bf16_f32 v159, v123, v124
	global_store_dwordx4 v[160:161], v[156:159], off
	v_cvt_pk_bf16_f32 v150, v118, v125
	v_cvt_pk_bf16_f32 v151, v119, v120
	v_cvt_pk_bf16_f32 v152, v114, v121
	v_cvt_pk_bf16_f32 v153, v115, v116
	global_store_dwordx4 v[160:161], v[150:153], off offset:256
	s_cbranch_vccnz .LBB0_230
	v_mul_f32_e32 v117, v148, v148
	v_fmac_f32_e32 v117, v126, v126
	v_mul_f32_e32 v126, v128, v128
	v_fmac_f32_e32 v126, v127, v127
	v_add_f32_e32 v117, v117, v126
	v_mul_f32_e32 v126, v129, v129
	v_fmac_f32_e32 v126, v122, v122
	v_mul_f32_e32 v122, v124, v124
	v_fmac_f32_e32 v122, v123, v123
	v_add_f32_e32 v122, v126, v122
	v_add_f32_e32 v117, v117, v122
	v_mul_f32_e32 v122, v125, v125
	v_fmac_f32_e32 v122, v118, v118
	v_mul_f32_e32 v118, v120, v120
	v_fmac_f32_e32 v118, v119, v119
	v_add_f32_e32 v118, v122, v118
	v_add_f32_e32 v117, v117, v118
	v_mul_f32_e32 v118, v121, v121
	v_fmac_f32_e32 v118, v114, v114
	v_mul_f32_e32 v114, v116, v116
	v_fmac_f32_e32 v114, v115, v115
	v_xor_b32_e32 v115, 16, v235
	v_add_u32_e32 v116, 64, v236
	v_cmp_lt_i32_e32 vcc, v115, v116
	v_add_f32_e32 v114, v118, v114
	v_add_f32_e32 v114, v114, v117
	v_cndmask_b32_e32 v115, v235, v115, vcc
	v_lshlrev_b32_e32 v115, 2, v115
	ds_bpermute_b32 v115, v115, v114
	s_waitcnt lgkmcnt(0)
	v_add_f32_e32 v114, v114, v115
	v_xor_b32_e32 v115, 32, v235
	v_cmp_lt_i32_e32 vcc, v115, v116
	s_nop 1
	v_cndmask_b32_e32 v115, v235, v115, vcc
	v_lshlrev_b32_e32 v115, 2, v115
	ds_bpermute_b32 v115, v115, v114
	s_and_saveexec_b64 s[8:9], s[40:41]
	s_cbranch_execz .LBB0_229
	s_waitcnt lgkmcnt(0)
	v_add_f32_e32 v114, v114, v115
	v_fma_f32 v114, v114, s88, 0.5
	v_trunc_f32_e32 v114, v114
	v_mul_f32_e32 v115, 0x2f800000, v114
	v_floor_f32_e32 v115, v115
	v_fmac_f32_e32 v114, 0xcf800000, v115
	v_cvt_u32_f32_e32 v114, v114
	v_cvt_u32_f32_e32 v115, v115
	v_lshl_add_u64 v[116:117], v[140:141], 3, s[36:37]
	global_atomic_add_x2 v[116:117], v[114:115], off

; __device__ __forceinline__ unsigned cvt_pk_bf16(float lo, float hi) { unsigned r; asm volatile("v_cvt_pk_bf16_f32 %0, %1, %2" : "=v"(r) : "v"(lo), "v"(hi)); return r; }
;     __device__ __forceinline__ void operator()(const f32x4 (&acc)[2][2][4][2], const Unit& u, int wr, int wc, int fr, int fq) const {
;         const int col0 = u.pn * BM + wc * 32 + 8 * fq;
; #pragma unroll
;         for (int ai = 0; ai < 2; ++ai)
; #pragma unroll
;             for (int m = 0; m < 4; ++m) { const int row = u.pm * BM + ai * HALF + wr * 64 + m * 16 + fr; bf16_t* xp = x + (size_t)row * ldc + col0;
;                 u32x4 bv[2];
; #pragma unroll
;                 for (int bj = 0; bj < 2; ++bj) bv[bj] = *(const u32x4*)(xp + bj * HALF);
;                 float sq = 0.f;
; #pragma unroll
;                 for (int bj = 0; bj < 2; ++bj) { u32x4 w;
; #pragma unroll
;                     for (int n = 0; n < 2; ++n) { const f32x4 a = acc[ai][bj][m][n]; const unsigned b0 = bv[bj][2 * n], b1 = bv[bj][2 * n + 1];
;                         const float o0 = __builtin_bit_cast(float, b0 << 16) + a[0], o1 = __builtin_bit_cast(float, b0 & 0xffff0000u) + a[1];
;                         const float o2 = __builtin_bit_cast(float, b1 << 16) + a[2], o3 = __builtin_bit_cast(float, b1 & 0xffff0000u) + a[3];
;                         sq += (o0 * o0 + o1 * o1) + (o2 * o2 + o3 * o3);
;                         w[2 * n] = cvt_pk_bf16(o0, o1); w[2 * n + 1] = cvt_pk_bf16(o2, o3); }
;                     *(u32x4*)(xp + bj * HALF) = w; }
;                 if (ss) { sq += __shfl_xor(sq, 16); sq += __shfl_xor(sq, 32); if (fq == 0) __hip_atomic_fetch_add(ss + row, (unsigned long long)(sq * 262144.f + 0.5f), __ATOMIC_RELAXED, __HIP_MEMORY_SCOPE_AGENT); } }
.LBB0_230:
	v_or_b32_e32 v114, 16, v140
	s_waitcnt lgkmcnt(0)
	v_ashrrev_i32_e32 v115, 31, v114
	v_lshlrev_b64 v[114:115], 12, v[114:115]
	v_lshl_add_u64 v[114:115], s[18:19], 0, v[114:115]
	v_lshl_add_u64 v[122:123], v[142:143], 1, v[114:115]
	s_and_b64 vcc, exec, s[44:45]
	s_waitcnt vmcnt(10)
	v_mov_b32_e32 v114, v170
	v_mov_b32_e32 v115, v171
	v_mov_b32_e32 v116, v172
	v_mov_b32_e32 v117, v173
	v_mov_b32_e32 v118, v174
	v_mov_b32_e32 v119, v175
	v_mov_b32_e32 v120, v176
	v_mov_b32_e32 v121, v177
	global_load_dwordx4 v[170:173], v[204:205], off
	global_load_dwordx4 v[174:177], v[204:205], off offset:256
	v_lshlrev_b32_e32 v124, 16, v114
	v_add_f32_e32 v110, v110, v124
	v_and_b32_e32 v114, 0xffff0000, v114
	v_lshlrev_b32_e32 v124, 16, v116
	v_and_b32_e32 v116, 0xffff0000, v116
	v_add_f32_e32 v111, v111, v114
	v_lshlrev_b32_e32 v114, 16, v115
	v_add_f32_e32 v107, v107, v116
	v_lshlrev_b32_e32 v116, 16, v117
	v_add_f32_e32 v112, v112, v114
	v_and_b32_e32 v114, 0xffff0000, v115
	v_add_f32_e32 v108, v108, v116
	v_and_b32_e32 v116, 0xffff0000, v117
	v_add_f32_e32 v113, v113, v114
	v_cvt_pk_bf16_f32 v114, v110, v111
	v_cvt_pk_bf16_f32 v115, v112, v113
	v_add_f32_e32 v106, v106, v124
	v_add_f32_e32 v109, v109, v116
	v_cvt_pk_bf16_f32 v116, v106, v107
	v_cvt_pk_bf16_f32 v117, v108, v109
	global_store_dwordx4 v[122:123], v[114:117], off
	s_nop 0
	s_nop 0
	v_lshlrev_b32_e32 v114, 16, v118
	v_lshlrev_b32_e32 v116, 16, v120
	v_add_f32_e32 v102, v102, v114
	v_and_b32_e32 v114, 0xffff0000, v118
	v_add_f32_e32 v98, v98, v116
	v_and_b32_e32 v116, 0xffff0000, v120
	v_add_f32_e32 v103, v103, v114
	v_lshlrev_b32_e32 v114, 16, v119
	v_add_f32_e32 v99, v99, v116
	v_lshlrev_b32_e32 v116, 16, v121
	v_add_f32_e32 v104, v104, v114
	v_and_b32_e32 v114, 0xffff0000, v119
	v_add_f32_e32 v100, v100, v116
	v_and_b32_e32 v116, 0xffff0000, v121
	v_add_f32_e32 v105, v105, v114
	v_add_f32_e32 v101, v101, v116
	v_cvt_pk_bf16_f32 v114, v102, v103
	v_cvt_pk_bf16_f32 v115, v104, v105
	v_cvt_pk_bf16_f32 v116, v98, v99
	v_cvt_pk_bf16_f32 v117, v100, v101
	global_store_dwordx4 v[122:123], v[114:117], off offset:256
	s_cbranch_vccnz .LBB0_234
	v_mul_f32_e32 v111, v111, v111
	v_mul_f32_e32 v107, v107, v107
	v_mul_f32_e32 v99, v99, v99
	v_fmac_f32_e32 v111, v110, v110
	v_mul_f32_e32 v110, v113, v113
	v_fmac_f32_e32 v107, v106, v106
	v_mul_f32_e32 v106, v109, v109
	v_mul_f32_e32 v103, v103, v103
	v_fmac_f32_e32 v99, v98, v98
	v_mul_f32_e32 v98, v101, v101
	v_fmac_f32_e32 v110, v112, v112
	v_fmac_f32_e32 v106, v108, v108
	v_fmac_f32_e32 v103, v102, v102
	v_mul_f32_e32 v102, v105, v105
	v_fmac_f32_e32 v98, v100, v100
	v_add_f32_e32 v110, v111, v110
	v_add_f32_e32 v106, v107, v106
	v_fmac_f32_e32 v102, v104, v104
	v_add_f32_e32 v98, v99, v98
	v_xor_b32_e32 v99, 16, v235
	v_add_u32_e32 v100, 64, v236
	v_add_f32_e32 v106, v110, v106
	v_add_f32_e32 v102, v103, v102
	v_cmp_lt_i32_e32 vcc, v99, v100
	v_add_f32_e32 v102, v106, v102
	v_add_f32_e32 v98, v98, v102
	v_cndmask_b32_e32 v99, v235, v99, vcc
	v_lshlrev_b32_e32 v99, 2, v99
	ds_bpermute_b32 v99, v99, v98
	s_waitcnt lgkmcnt(0)
	v_add_f32_e32 v98, v98, v99
	v_xor_b32_e32 v99, 32, v235
	v_cmp_lt_i32_e32 vcc, v99, v100
	s_nop 1
	v_cndmask_b32_e32 v99, v235, v99, vcc
	v_lshlrev_b32_e32 v99, 2, v99
	ds_bpermute_b32 v99, v99, v98
	s_and_saveexec_b64 s[8:9], s[40:41]
	s_cbranch_execz .LBB0_233
	s_waitcnt lgkmcnt(0)
	v_add_f32_e32 v98, v98, v99
	v_fma_f32 v98, v98, s88, 0.5
	v_trunc_f32_e32 v98, v98
	v_mul_f32_e32 v99, 0x2f800000, v98
	v_floor_f32_e32 v99, v99
	v_fmac_f32_e32 v98, 0xcf800000, v99
	v_cvt_u32_f32_e32 v98, v98
	v_cvt_u32_f32_e32 v99, v99
	v_lshl_add_u64 v[100:101], v[140:141], 3, s[36:37]
	global_atomic_add_x2 v[100:101], v[98:99], off offset:128

; __device__ __forceinline__ unsigned cvt_pk_bf16(float lo, float hi) { unsigned r; asm volatile("v_cvt_pk_bf16_f32 %0, %1, %2" : "=v"(r) : "v"(lo), "v"(hi)); return r; }
;     __device__ __forceinline__ void operator()(const f32x4 (&acc)[2][2][4][2], const Unit& u, int wr, int wc, int fr, int fq) const {
;         const int col0 = u.pn * BM + wc * 32 + 8 * fq;
; #pragma unroll
;         for (int ai = 0; ai < 2; ++ai)
; #pragma unroll
;             for (int m = 0; m < 4; ++m) { const int row = u.pm * BM + ai * HALF + wr * 64 + m * 16 + fr; bf16_t* xp = x + (size_t)row * ldc + col0;
;                 u32x4 bv[2];
; #pragma unroll
;                 for (int bj = 0; bj < 2; ++bj) bv[bj] = *(const u32x4*)(xp + bj * HALF);
;                 float sq = 0.f;
; #pragma unroll
;                 for (int bj = 0; bj < 2; ++bj) { u32x4 w;
; #pragma unroll
;                     for (int n = 0; n < 2; ++n) { const f32x4 a = acc[ai][bj][m][n]; const unsigned b0 = bv[bj][2 * n], b1 = bv[bj][2 * n + 1];
;                         const float o0 = __builtin_bit_cast(float, b0 << 16) + a[0], o1 = __builtin_bit_cast(float, b0 & 0xffff0000u) + a[1];
;                         const float o2 = __builtin_bit_cast(float, b1 << 16) + a[2], o3 = __builtin_bit_cast(float, b1 & 0xffff0000u) + a[3];
;                         sq += (o0 * o0 + o1 * o1) + (o2 * o2 + o3 * o3);
;                         w[2 * n] = cvt_pk_bf16(o0, o1); w[2 * n + 1] = cvt_pk_bf16(o2, o3); }
;                     *(u32x4*)(xp + bj * HALF) = w; }
;                 if (ss) { sq += __shfl_xor(sq, 16); sq += __shfl_xor(sq, 32); if (fq == 0) __hip_atomic_fetch_add(ss + row, (unsigned long long)(sq * 262144.f + 0.5f), __ATOMIC_RELAXED, __HIP_MEMORY_SCOPE_AGENT); } }
.LBB0_234:
	v_or_b32_e32 v98, 32, v140
	s_waitcnt lgkmcnt(0)
	v_ashrrev_i32_e32 v99, 31, v98
	v_lshlrev_b64 v[98:99], 12, v[98:99]
	v_lshl_add_u64 v[98:99], s[18:19], 0, v[98:99]
	v_lshl_add_u64 v[106:107], v[142:143], 1, v[98:99]
	s_and_b64 vcc, exec, s[44:45]
	s_waitcnt vmcnt(12)
	v_mov_b32_e32 v98, v178
	v_mov_b32_e32 v99, v179
	v_mov_b32_e32 v100, v180
	v_mov_b32_e32 v101, v181
	v_mov_b32_e32 v102, v182
	v_mov_b32_e32 v103, v183
	v_mov_b32_e32 v104, v184
	v_mov_b32_e32 v105, v185
	global_load_dwordx4 v[178:181], v[206:207], off
	global_load_dwordx4 v[182:185], v[206:207], off offset:256
	v_lshlrev_b32_e32 v108, 16, v98
	v_add_f32_e32 v94, v94, v108
	v_and_b32_e32 v98, 0xffff0000, v98
	v_lshlrev_b32_e32 v108, 16, v100
	v_and_b32_e32 v100, 0xffff0000, v100
	v_add_f32_e32 v95, v95, v98
	v_lshlrev_b32_e32 v98, 16, v99
	v_add_f32_e32 v91, v91, v100
	v_lshlrev_b32_e32 v100, 16, v101
	v_add_f32_e32 v96, v96, v98
	v_and_b32_e32 v98, 0xffff0000, v99
	v_add_f32_e32 v92, v92, v100
	v_and_b32_e32 v100, 0xffff0000, v101
	v_add_f32_e32 v97, v97, v98
	v_cvt_pk_bf16_f32 v98, v94, v95
	v_cvt_pk_bf16_f32 v99, v96, v97
	v_add_f32_e32 v90, v90, v108
	v_add_f32_e32 v93, v93, v100
	v_cvt_pk_bf16_f32 v100, v90, v91
	v_cvt_pk_bf16_f32 v101, v92, v93
	global_store_dwordx4 v[106:107], v[98:101], off
	s_nop 0
	s_nop 0
	v_lshlrev_b32_e32 v98, 16, v102
	v_lshlrev_b32_e32 v100, 16, v104
	v_add_f32_e32 v86, v86, v98
	v_and_b32_e32 v98, 0xffff0000, v102
	v_add_f32_e32 v82, v82, v100
	v_and_b32_e32 v100, 0xffff0000, v104
	v_add_f32_e32 v87, v87, v98
	v_lshlrev_b32_e32 v98, 16, v103
	v_add_f32_e32 v83, v83, v100
	v_lshlrev_b32_e32 v100, 16, v105
	v_add_f32_e32 v88, v88, v98
	v_and_b32_e32 v98, 0xffff0000, v103
	v_add_f32_e32 v84, v84, v100
	v_and_b32_e32 v100, 0xffff0000, v105
	v_add_f32_e32 v89, v89, v98
	v_add_f32_e32 v85, v85, v100
	v_cvt_pk_bf16_f32 v98, v86, v87
	v_cvt_pk_bf16_f32 v99, v88, v89
	v_cvt_pk_bf16_f32 v100, v82, v83
	v_cvt_pk_bf16_f32 v101, v84, v85
	global_store_dwordx4 v[106:107], v[98:101], off offset:256
	s_cbranch_vccnz .LBB0_238
	v_mul_f32_e32 v95, v95, v95
	v_mul_f32_e32 v91, v91, v91
	v_mul_f32_e32 v83, v83, v83
	v_fmac_f32_e32 v95, v94, v94
	v_mul_f32_e32 v94, v97, v97
	v_fmac_f32_e32 v91, v90, v90
	v_mul_f32_e32 v90, v93, v93
	v_mul_f32_e32 v87, v87, v87
	v_fmac_f32_e32 v83, v82, v82
	v_mul_f32_e32 v82, v85, v85
	v_fmac_f32_e32 v94, v96, v96
	v_fmac_f32_e32 v90, v92, v92
	v_fmac_f32_e32 v87, v86, v86
	v_mul_f32_e32 v86, v89, v89
	v_fmac_f32_e32 v82, v84, v84
	v_add_f32_e32 v94, v95, v94
	v_add_f32_e32 v90, v91, v90
	v_fmac_f32_e32 v86, v88, v88
	v_add_f32_e32 v82, v83, v82
	v_xor_b32_e32 v83, 16, v235
	v_add_u32_e32 v84, 64, v236
	v_add_f32_e32 v90, v94, v90
	v_add_f32_e32 v86, v87, v86
	v_cmp_lt_i32_e32 vcc, v83, v84
	v_add_f32_e32 v86, v90, v86
	v_add_f32_e32 v82, v82, v86
	v_cndmask_b32_e32 v83, v235, v83, vcc
	v_lshlrev_b32_e32 v83, 2, v83
	ds_bpermute_b32 v83, v83, v82
	s_waitcnt lgkmcnt(0)
	v_add_f32_e32 v82, v82, v83
	v_xor_b32_e32 v83, 32, v235
	v_cmp_lt_i32_e32 vcc, v83, v84
	s_nop 1
	v_cndmask_b32_e32 v83, v235, v83, vcc
	v_lshlrev_b32_e32 v83, 2, v83
	ds_bpermute_b32 v83, v83, v82
	s_and_saveexec_b64 s[8:9], s[40:41]
	s_cbranch_execz .LBB0_237
	s_waitcnt lgkmcnt(0)
	v_add_f32_e32 v82, v82, v83
	v_fma_f32 v82, v82, s88, 0.5
	v_trunc_f32_e32 v82, v82
	v_mul_f32_e32 v83, 0x2f800000, v82
	v_floor_f32_e32 v83, v83
	v_fmac_f32_e32 v82, 0xcf800000, v83
	v_cvt_u32_f32_e32 v82, v82
	v_cvt_u32_f32_e32 v83, v83
	v_lshl_add_u64 v[84:85], v[140:141], 3, s[36:37]
	global_atomic_add_x2 v[84:85], v[82:83], off offset:256

; __device__ __forceinline__ unsigned cvt_pk_bf16(float lo, float hi) { unsigned r; asm volatile("v_cvt_pk_bf16_f32 %0, %1, %2" : "=v"(r) : "v"(lo), "v"(hi)); return r; }
;     __device__ __forceinline__ void operator()(const f32x4 (&acc)[2][2][4][2], const Unit& u, int wr, int wc, int fr, int fq) const {
;         const int col0 = u.pn * BM + wc * 32 + 8 * fq;
; #pragma unroll
;         for (int ai = 0; ai < 2; ++ai)
; #pragma unroll
;             for (int m = 0; m < 4; ++m) { const int row = u.pm * BM + ai * HALF + wr * 64 + m * 16 + fr; bf16_t* xp = x + (size_t)row * ldc + col0;
;                 u32x4 bv[2];
; #pragma unroll
;                 for (int bj = 0; bj < 2; ++bj) bv[bj] = *(const u32x4*)(xp + bj * HALF);
;                 float sq = 0.f;
; #pragma unroll
;                 for (int bj = 0; bj < 2; ++bj) { u32x4 w;
; #pragma unroll
;                     for (int n = 0; n < 2; ++n) { const f32x4 a = acc[ai][bj][m][n]; const unsigned b0 = bv[bj][2 * n], b1 = bv[bj][2 * n + 1];
;                         const float o0 = __builtin_bit_cast(float, b0 << 16) + a[0], o1 = __builtin_bit_cast(float, b0 & 0xffff0000u) + a[1];
;                         const float o2 = __builtin_bit_cast(float, b1 << 16) + a[2], o3 = __builtin_bit_cast(float, b1 & 0xffff0000u) + a[3];
;                         sq += (o0 * o0 + o1 * o1) + (o2 * o2 + o3 * o3);
;                         w[2 * n] = cvt_pk_bf16(o0, o1); w[2 * n + 1] = cvt_pk_bf16(o2, o3); }
;                     *(u32x4*)(xp + bj * HALF) = w; }
;                 if (ss) { sq += __shfl_xor(sq, 16); sq += __shfl_xor(sq, 32); if (fq == 0) __hip_atomic_fetch_add(ss + row, (unsigned long long)(sq * 262144.f + 0.5f), __ATOMIC_RELAXED, __HIP_MEMORY_SCOPE_AGENT); } }
.LBB0_238:
	v_or_b32_e32 v82, 48, v140
	s_waitcnt lgkmcnt(0)
	v_ashrrev_i32_e32 v83, 31, v82
	v_lshlrev_b64 v[82:83], 12, v[82:83]
	v_lshl_add_u64 v[82:83], s[18:19], 0, v[82:83]
	v_lshl_add_u64 v[90:91], v[142:143], 1, v[82:83]
	s_and_b64 vcc, exec, s[44:45]
	s_waitcnt vmcnt(14)
	v_mov_b32_e32 v82, v186
	v_mov_b32_e32 v83, v187
	v_mov_b32_e32 v84, v188
	v_mov_b32_e32 v85, v189
	v_mov_b32_e32 v86, v190
	v_mov_b32_e32 v87, v191
	v_mov_b32_e32 v88, v192
	v_mov_b32_e32 v89, v193
	v_lshlrev_b32_e32 v92, 16, v82
	v_add_f32_e32 v78, v78, v92
	v_and_b32_e32 v82, 0xffff0000, v82
	v_lshlrev_b32_e32 v92, 16, v84
	v_and_b32_e32 v84, 0xffff0000, v84
	v_add_f32_e32 v79, v79, v82
	v_lshlrev_b32_e32 v82, 16, v83
	v_add_f32_e32 v75, v75, v84
	v_lshlrev_b32_e32 v84, 16, v85
	v_add_f32_e32 v80, v80, v82
	v_and_b32_e32 v82, 0xffff0000, v83
	v_add_f32_e32 v76, v76, v84
	v_and_b32_e32 v84, 0xffff0000, v85
	v_add_f32_e32 v81, v81, v82
	v_cvt_pk_bf16_f32 v82, v78, v79
	v_cvt_pk_bf16_f32 v83, v80, v81
	v_add_f32_e32 v74, v74, v92
	v_add_f32_e32 v77, v77, v84
	v_cvt_pk_bf16_f32 v84, v74, v75
	v_cvt_pk_bf16_f32 v85, v76, v77
	global_store_dwordx4 v[90:91], v[82:85], off
	s_nop 0
	s_nop 0
	v_lshlrev_b32_e32 v82, 16, v86
	v_lshlrev_b32_e32 v84, 16, v88
	v_add_f32_e32 v70, v70, v82
	v_and_b32_e32 v82, 0xffff0000, v86
	v_add_f32_e32 v66, v66, v84
	v_and_b32_e32 v84, 0xffff0000, v88
	v_add_f32_e32 v71, v71, v82
	v_lshlrev_b32_e32 v82, 16, v87
	v_add_f32_e32 v67, v67, v84
	v_lshlrev_b32_e32 v84, 16, v89
	v_add_f32_e32 v72, v72, v82
	v_and_b32_e32 v82, 0xffff0000, v87
	v_add_f32_e32 v68, v68, v84
	v_and_b32_e32 v84, 0xffff0000, v89
	v_add_f32_e32 v73, v73, v82
	v_add_f32_e32 v69, v69, v84
	v_cvt_pk_bf16_f32 v82, v70, v71
	v_cvt_pk_bf16_f32 v83, v72, v73
	v_cvt_pk_bf16_f32 v84, v66, v67
	v_cvt_pk_bf16_f32 v85, v68, v69
	global_store_dwordx4 v[90:91], v[82:85], off offset:256
	s_cbranch_vccnz .LBB0_242
	v_mul_f32_e32 v79, v79, v79
	v_mul_f32_e32 v75, v75, v75
	v_mul_f32_e32 v67, v67, v67
	v_fmac_f32_e32 v79, v78, v78
	v_mul_f32_e32 v78, v81, v81
	v_fmac_f32_e32 v75, v74, v74
	v_mul_f32_e32 v74, v77, v77
	v_mul_f32_e32 v71, v71, v71
	v_fmac_f32_e32 v67, v66, v66
	v_mul_f32_e32 v66, v69, v69
	v_fmac_f32_e32 v78, v80, v80
	v_fmac_f32_e32 v74, v76, v76
	v_fmac_f32_e32 v71, v70, v70
	v_mul_f32_e32 v70, v73, v73
	v_fmac_f32_e32 v66, v68, v68
	v_add_f32_e32 v78, v79, v78
	v_add_f32_e32 v74, v75, v74
	v_fmac_f32_e32 v70, v72, v72
	v_add_f32_e32 v66, v67, v66
	v_xor_b32_e32 v67, 16, v235
	v_add_u32_e32 v68, 64, v236
	v_add_f32_e32 v74, v78, v74
	v_add_f32_e32 v70, v71, v70
	v_cmp_lt_i32_e32 vcc, v67, v68
	v_add_f32_e32 v70, v74, v70
	v_add_f32_e32 v66, v66, v70
	v_cndmask_b32_e32 v67, v235, v67, vcc
	v_lshlrev_b32_e32 v67, 2, v67
	ds_bpermute_b32 v67, v67, v66
	s_waitcnt lgkmcnt(0)
	v_add_f32_e32 v66, v66, v67
	v_xor_b32_e32 v67, 32, v235
	v_cmp_lt_i32_e32 vcc, v67, v68
	s_nop 1
	v_cndmask_b32_e32 v67, v235, v67, vcc
	v_lshlrev_b32_e32 v67, 2, v67
	ds_bpermute_b32 v67, v67, v66
	s_and_saveexec_b64 s[8:9], s[40:41]
	s_cbranch_execz .LBB0_241
	s_waitcnt lgkmcnt(0)
	v_add_f32_e32 v66, v66, v67
	v_fma_f32 v66, v66, s88, 0.5
	v_trunc_f32_e32 v66, v66
	v_mul_f32_e32 v67, 0x2f800000, v66
	v_floor_f32_e32 v67, v67
	v_fmac_f32_e32 v66, 0xcf800000, v67
	v_cvt_u32_f32_e32 v66, v66
	v_cvt_u32_f32_e32 v67, v67
	v_lshl_add_u64 v[68:69], v[140:141], 3, s[36:37]
	global_atomic_add_x2 v[68:69], v[66:67], off offset:384

; __device__ __forceinline__ unsigned cvt_pk_bf16(float lo, float hi) { unsigned r; asm volatile("v_cvt_pk_bf16_f32 %0, %1, %2" : "=v"(r) : "v"(lo), "v"(hi)); return r; }
;     __device__ __forceinline__ void operator()(const f32x4 (&acc)[2][2][4][2], const Unit& u, int wr, int wc, int fr, int fq) const {
;         const int col0 = u.pn * BM + wc * 32 + 8 * fq;
; #pragma unroll
;         for (int ai = 0; ai < 2; ++ai)
; #pragma unroll
;             for (int m = 0; m < 4; ++m) { const int row = u.pm * BM + ai * HALF + wr * 64 + m * 16 + fr; bf16_t* xp = x + (size_t)row * ldc + col0;
;                 u32x4 bv[2];
; #pragma unroll
;                 for (int bj = 0; bj < 2; ++bj) bv[bj] = *(const u32x4*)(xp + bj * HALF);
;                 float sq = 0.f;
; #pragma unroll
;                 for (int bj = 0; bj < 2; ++bj) { u32x4 w;
; #pragma unroll
;                     for (int n = 0; n < 2; ++n) { const f32x4 a = acc[ai][bj][m][n]; const unsigned b0 = bv[bj][2 * n], b1 = bv[bj][2 * n + 1];
;                         const float o0 = __builtin_bit_cast(float, b0 << 16) + a[0], o1 = __builtin_bit_cast(float, b0 & 0xffff0000u) + a[1];
;                         const float o2 = __builtin_bit_cast(float, b1 << 16) + a[2], o3 = __builtin_bit_cast(float, b1 & 0xffff0000u) + a[3];
;                         sq += (o0 * o0 + o1 * o1) + (o2 * o2 + o3 * o3);
;                         w[2 * n] = cvt_pk_bf16(o0, o1); w[2 * n + 1] = cvt_pk_bf16(o2, o3); }
;                     *(u32x4*)(xp + bj * HALF) = w; }
;                 if (ss) { sq += __shfl_xor(sq, 16); sq += __shfl_xor(sq, 32); if (fq == 0) __hip_atomic_fetch_add(ss + row, (unsigned long long)(sq * 262144.f + 0.5f), __ATOMIC_RELAXED, __HIP_MEMORY_SCOPE_AGENT); } }
.LBB0_242:
	v_add_u32_e32 v66, 0x80, v140
	s_waitcnt lgkmcnt(0)
	v_ashrrev_i32_e32 v67, 31, v66
	v_lshlrev_b64 v[66:67], 12, v[66:67]
	v_lshl_add_u64 v[66:67], s[18:19], 0, v[66:67]
	v_lshl_add_u64 v[74:75], v[142:143], 1, v[66:67]
	s_and_b64 vcc, exec, s[44:45]
	s_waitcnt vmcnt(14)
	v_mov_b32_e32 v66, v194
	v_mov_b32_e32 v67, v195
	v_mov_b32_e32 v68, v196
	v_mov_b32_e32 v69, v197
	v_mov_b32_e32 v70, v198
	v_mov_b32_e32 v71, v199
	v_mov_b32_e32 v72, v200
	v_mov_b32_e32 v73, v201
	v_lshlrev_b32_e32 v76, 16, v66
	v_add_f32_e32 v62, v62, v76
	v_and_b32_e32 v66, 0xffff0000, v66
	v_lshlrev_b32_e32 v76, 16, v68
	v_and_b32_e32 v68, 0xffff0000, v68
	v_add_f32_e32 v63, v63, v66
	v_lshlrev_b32_e32 v66, 16, v67
	v_add_f32_e32 v59, v59, v68
	v_lshlrev_b32_e32 v68, 16, v69
	v_add_f32_e32 v64, v64, v66
	v_and_b32_e32 v66, 0xffff0000, v67
	v_add_f32_e32 v60, v60, v68
	v_and_b32_e32 v68, 0xffff0000, v69
	v_add_f32_e32 v65, v65, v66
	v_cvt_pk_bf16_f32 v66, v62, v63
	v_cvt_pk_bf16_f32 v67, v64, v65
	v_add_f32_e32 v58, v58, v76
	v_add_f32_e32 v61, v61, v68
	v_cvt_pk_bf16_f32 v68, v58, v59
	v_cvt_pk_bf16_f32 v69, v60, v61
	global_store_dwordx4 v[74:75], v[66:69], off
	s_nop 0
	s_nop 0
	v_lshlrev_b32_e32 v66, 16, v70
	v_lshlrev_b32_e32 v68, 16, v72
	v_add_f32_e32 v54, v54, v66
	v_and_b32_e32 v66, 0xffff0000, v70
	v_add_f32_e32 v50, v50, v68
	v_and_b32_e32 v68, 0xffff0000, v72
	v_add_f32_e32 v55, v55, v66
	v_lshlrev_b32_e32 v66, 16, v71
	v_add_f32_e32 v51, v51, v68
	v_lshlrev_b32_e32 v68, 16, v73
	v_add_f32_e32 v56, v56, v66
	v_and_b32_e32 v66, 0xffff0000, v71
	v_add_f32_e32 v52, v52, v68
	v_and_b32_e32 v68, 0xffff0000, v73
	v_add_f32_e32 v57, v57, v66
	v_add_f32_e32 v53, v53, v68
	v_cvt_pk_bf16_f32 v66, v54, v55
	v_cvt_pk_bf16_f32 v67, v56, v57
	v_cvt_pk_bf16_f32 v68, v50, v51
	v_cvt_pk_bf16_f32 v69, v52, v53
	global_store_dwordx4 v[74:75], v[66:69], off offset:256
	s_cbranch_vccnz .LBB0_246
	v_mul_f32_e32 v63, v63, v63
	v_mul_f32_e32 v59, v59, v59
	v_mul_f32_e32 v51, v51, v51
	v_fmac_f32_e32 v63, v62, v62
	v_mul_f32_e32 v62, v65, v65
	v_fmac_f32_e32 v59, v58, v58
	v_mul_f32_e32 v58, v61, v61
	v_mul_f32_e32 v55, v55, v55
	v_fmac_f32_e32 v51, v50, v50
	v_mul_f32_e32 v50, v53, v53
	v_fmac_f32_e32 v62, v64, v64
	v_fmac_f32_e32 v58, v60, v60
	v_fmac_f32_e32 v55, v54, v54
	v_mul_f32_e32 v54, v57, v57
	v_fmac_f32_e32 v50, v52, v52
	v_add_f32_e32 v62, v63, v62
	v_add_f32_e32 v58, v59, v58
	v_fmac_f32_e32 v54, v56, v56
	v_add_f32_e32 v50, v51, v50
	v_xor_b32_e32 v51, 16, v235
	v_add_u32_e32 v52, 64, v236
	v_add_f32_e32 v58, v62, v58
	v_add_f32_e32 v54, v55, v54
	v_cmp_lt_i32_e32 vcc, v51, v52
	v_add_f32_e32 v54, v58, v54
	v_add_f32_e32 v50, v50, v54
	v_cndmask_b32_e32 v51, v235, v51, vcc
	v_lshlrev_b32_e32 v51, 2, v51
	ds_bpermute_b32 v51, v51, v50
	s_waitcnt lgkmcnt(0)
	v_add_f32_e32 v50, v50, v51
	v_xor_b32_e32 v51, 32, v235
	v_cmp_lt_i32_e32 vcc, v51, v52
	s_nop 1
	v_cndmask_b32_e32 v51, v235, v51, vcc
	v_lshlrev_b32_e32 v51, 2, v51
	ds_bpermute_b32 v51, v51, v50
	s_and_saveexec_b64 s[8:9], s[40:41]
	s_cbranch_execz .LBB0_245
	s_waitcnt lgkmcnt(0)
	v_add_f32_e32 v50, v50, v51
	v_fma_f32 v50, v50, s88, 0.5
	v_trunc_f32_e32 v50, v50
	v_mul_f32_e32 v51, 0x2f800000, v50
	v_floor_f32_e32 v51, v51
	v_fmac_f32_e32 v50, 0xcf800000, v51
	v_cvt_u32_f32_e32 v50, v50
	v_cvt_u32_f32_e32 v51, v51
	v_lshl_add_u64 v[52:53], v[140:141], 3, s[36:37]
	global_atomic_add_x2 v[52:53], v[50:51], off offset:1024

; __device__ __forceinline__ unsigned cvt_pk_bf16(float lo, float hi) { unsigned r; asm volatile("v_cvt_pk_bf16_f32 %0, %1, %2" : "=v"(r) : "v"(lo), "v"(hi)); return r; }
;     __device__ __forceinline__ void operator()(const f32x4 (&acc)[2][2][4][2], const Unit& u, int wr, int wc, int fr, int fq) const {
;         const int col0 = u.pn * BM + wc * 32 + 8 * fq;
; #pragma unroll
;         for (int ai = 0; ai < 2; ++ai)
; #pragma unroll
;             for (int m = 0; m < 4; ++m) { const int row = u.pm * BM + ai * HALF + wr * 64 + m * 16 + fr; bf16_t* xp = x + (size_t)row * ldc + col0;
;                 u32x4 bv[2];
; #pragma unroll
;                 for (int bj = 0; bj < 2; ++bj) bv[bj] = *(const u32x4*)(xp + bj * HALF);
;                 float sq = 0.f;
; #pragma unroll
;                 for (int bj = 0; bj < 2; ++bj) { u32x4 w;
; #pragma unroll
;                     for (int n = 0; n < 2; ++n) { const f32x4 a = acc[ai][bj][m][n]; const unsigned b0 = bv[bj][2 * n], b1 = bv[bj][2 * n + 1];
;                         const float o0 = __builtin_bit_cast(float, b0 << 16) + a[0], o1 = __builtin_bit_cast(float, b0 & 0xffff0000u) + a[1];
;                         const float o2 = __builtin_bit_cast(float, b1 << 16) + a[2], o3 = __builtin_bit_cast(float, b1 & 0xffff0000u) + a[3];
;                         sq += (o0 * o0 + o1 * o1) + (o2 * o2 + o3 * o3);
;                         w[2 * n] = cvt_pk_bf16(o0, o1); w[2 * n + 1] = cvt_pk_bf16(o2, o3); }
;                     *(u32x4*)(xp + bj * HALF) = w; }
;                 if (ss) { sq += __shfl_xor(sq, 16); sq += __shfl_xor(sq, 32); if (fq == 0) __hip_atomic_fetch_add(ss + row, (unsigned long long)(sq * 262144.f + 0.5f), __ATOMIC_RELAXED, __HIP_MEMORY_SCOPE_AGENT); } }
.LBB0_246:
	v_add_u32_e32 v50, 0x90, v140
	s_waitcnt lgkmcnt(0)
	v_ashrrev_i32_e32 v51, 31, v50
	v_lshlrev_b64 v[50:51], 12, v[50:51]
	v_lshl_add_u64 v[50:51], s[18:19], 0, v[50:51]
	v_lshl_add_u64 v[58:59], v[142:143], 1, v[50:51]
	s_and_b64 vcc, exec, s[44:45]
	s_waitcnt vmcnt(14)
	v_mov_b32_e32 v50, v162
	v_mov_b32_e32 v51, v163
	v_mov_b32_e32 v52, v164
	v_mov_b32_e32 v53, v165
	v_mov_b32_e32 v54, v166
	v_mov_b32_e32 v55, v167
	v_mov_b32_e32 v56, v168
	v_mov_b32_e32 v57, v169
	v_lshlrev_b32_e32 v60, 16, v50
	v_add_f32_e32 v46, v46, v60
	v_and_b32_e32 v50, 0xffff0000, v50
	v_lshlrev_b32_e32 v60, 16, v52
	v_and_b32_e32 v52, 0xffff0000, v52
	v_add_f32_e32 v47, v47, v50
	v_lshlrev_b32_e32 v50, 16, v51
	v_add_f32_e32 v43, v43, v52
	v_lshlrev_b32_e32 v52, 16, v53
	v_add_f32_e32 v48, v48, v50
	v_and_b32_e32 v50, 0xffff0000, v51
	v_add_f32_e32 v44, v44, v52
	v_and_b32_e32 v52, 0xffff0000, v53
	v_add_f32_e32 v49, v49, v50
	v_cvt_pk_bf16_f32 v50, v46, v47
	v_cvt_pk_bf16_f32 v51, v48, v49
	v_add_f32_e32 v42, v42, v60
	v_add_f32_e32 v45, v45, v52
	v_cvt_pk_bf16_f32 v52, v42, v43
	v_cvt_pk_bf16_f32 v53, v44, v45
	global_store_dwordx4 v[58:59], v[50:53], off
	s_nop 0
	s_nop 0
	v_lshlrev_b32_e32 v50, 16, v54
	v_lshlrev_b32_e32 v52, 16, v56
	v_add_f32_e32 v38, v38, v50
	v_and_b32_e32 v50, 0xffff0000, v54
	v_add_f32_e32 v34, v34, v52
	v_and_b32_e32 v52, 0xffff0000, v56
	v_add_f32_e32 v39, v39, v50
	v_lshlrev_b32_e32 v50, 16, v55
	v_add_f32_e32 v35, v35, v52
	v_lshlrev_b32_e32 v52, 16, v57
	v_add_f32_e32 v40, v40, v50
	v_and_b32_e32 v50, 0xffff0000, v55
	v_add_f32_e32 v36, v36, v52
	v_and_b32_e32 v52, 0xffff0000, v57
	v_add_f32_e32 v41, v41, v50
	v_add_f32_e32 v37, v37, v52
	v_cvt_pk_bf16_f32 v50, v38, v39
	v_cvt_pk_bf16_f32 v51, v40, v41
	v_cvt_pk_bf16_f32 v52, v34, v35
	v_cvt_pk_bf16_f32 v53, v36, v37
	global_store_dwordx4 v[58:59], v[50:53], off offset:256
	s_cbranch_vccnz .LBB0_250
	v_mul_f32_e32 v47, v47, v47
	v_mul_f32_e32 v43, v43, v43
	v_mul_f32_e32 v35, v35, v35
	v_fmac_f32_e32 v47, v46, v46
	v_mul_f32_e32 v46, v49, v49
	v_fmac_f32_e32 v43, v42, v42
	v_mul_f32_e32 v42, v45, v45
	v_mul_f32_e32 v39, v39, v39
	v_fmac_f32_e32 v35, v34, v34
	v_mul_f32_e32 v34, v37, v37
	v_fmac_f32_e32 v46, v48, v48
	v_fmac_f32_e32 v42, v44, v44
	v_fmac_f32_e32 v39, v38, v38
	v_mul_f32_e32 v38, v41, v41
	v_fmac_f32_e32 v34, v36, v36
	v_add_f32_e32 v46, v47, v46
	v_add_f32_e32 v42, v43, v42
	v_fmac_f32_e32 v38, v40, v40
	v_add_f32_e32 v34, v35, v34
	v_xor_b32_e32 v35, 16, v235
	v_add_u32_e32 v36, 64, v236
	v_add_f32_e32 v42, v46, v42
	v_add_f32_e32 v38, v39, v38
	v_cmp_lt_i32_e32 vcc, v35, v36
	v_add_f32_e32 v38, v42, v38
	v_add_f32_e32 v34, v34, v38
	v_cndmask_b32_e32 v35, v235, v35, vcc
	v_lshlrev_b32_e32 v35, 2, v35
	ds_bpermute_b32 v35, v35, v34
	s_waitcnt lgkmcnt(0)
	v_add_f32_e32 v34, v34, v35
	v_xor_b32_e32 v35, 32, v235
	v_cmp_lt_i32_e32 vcc, v35, v36
	s_nop 1
	v_cndmask_b32_e32 v35, v235, v35, vcc
	v_lshlrev_b32_e32 v35, 2, v35
	ds_bpermute_b32 v35, v35, v34
	s_and_saveexec_b64 s[8:9], s[40:41]
	s_cbranch_execz .LBB0_249
	s_waitcnt lgkmcnt(0)
	v_add_f32_e32 v34, v34, v35
	v_fma_f32 v34, v34, s88, 0.5
	v_trunc_f32_e32 v34, v34
	v_mul_f32_e32 v35, 0x2f800000, v34
	v_floor_f32_e32 v35, v35
	v_fmac_f32_e32 v34, 0xcf800000, v35
	v_cvt_u32_f32_e32 v34, v34
	v_cvt_u32_f32_e32 v35, v35
	v_lshl_add_u64 v[36:37], v[140:141], 3, s[36:37]
	global_atomic_add_x2 v[36:37], v[34:35], off offset:1152

; __device__ __forceinline__ unsigned cvt_pk_bf16(float lo, float hi) { unsigned r; asm volatile("v_cvt_pk_bf16_f32 %0, %1, %2" : "=v"(r) : "v"(lo), "v"(hi)); return r; }
;     __device__ __forceinline__ void operator()(const f32x4 (&acc)[2][2][4][2], const Unit& u, int wr, int wc, int fr, int fq) const {
;         const int col0 = u.pn * BM + wc * 32 + 8 * fq;
; #pragma unroll
;         for (int ai = 0; ai < 2; ++ai)
; #pragma unroll
;             for (int m = 0; m < 4; ++m) { const int row = u.pm * BM + ai * HALF + wr * 64 + m * 16 + fr; bf16_t* xp = x + (size_t)row * ldc + col0;
;                 u32x4 bv[2];
; #pragma unroll
;                 for (int bj = 0; bj < 2; ++bj) bv[bj] = *(const u32x4*)(xp + bj * HALF);
;                 float sq = 0.f;
; #pragma unroll
;                 for (int bj = 0; bj < 2; ++bj) { u32x4 w;
; #pragma unroll
;                     for (int n = 0; n < 2; ++n) { const f32x4 a = acc[ai][bj][m][n]; const unsigned b0 = bv[bj][2 * n], b1 = bv[bj][2 * n + 1];
;                         const float o0 = __builtin_bit_cast(float, b0 << 16) + a[0], o1 = __builtin_bit_cast(float, b0 & 0xffff0000u) + a[1];
;                         const float o2 = __builtin_bit_cast(float, b1 << 16) + a[2], o3 = __builtin_bit_cast(float, b1 & 0xffff0000u) + a[3];
;                         sq += (o0 * o0 + o1 * o1) + (o2 * o2 + o3 * o3);
;                         w[2 * n] = cvt_pk_bf16(o0, o1); w[2 * n + 1] = cvt_pk_bf16(o2, o3); }
;                     *(u32x4*)(xp + bj * HALF) = w; }
;                 if (ss) { sq += __shfl_xor(sq, 16); sq += __shfl_xor(sq, 32); if (fq == 0) __hip_atomic_fetch_add(ss + row, (unsigned long long)(sq * 262144.f + 0.5f), __ATOMIC_RELAXED, __HIP_MEMORY_SCOPE_AGENT); } }
.LBB0_250:
	v_add_u32_e32 v34, 0xa0, v140
	s_waitcnt lgkmcnt(0)
	v_ashrrev_i32_e32 v35, 31, v34
	v_lshlrev_b64 v[34:35], 12, v[34:35]
	v_lshl_add_u64 v[34:35], s[18:19], 0, v[34:35]
	v_lshl_add_u64 v[42:43], v[142:143], 1, v[34:35]
	s_and_b64 vcc, exec, s[44:45]
	s_waitcnt vmcnt(12)
	v_mov_b32_e32 v34, v170
	v_mov_b32_e32 v35, v171
	v_mov_b32_e32 v36, v172
	v_mov_b32_e32 v37, v173
	v_mov_b32_e32 v38, v174
	v_mov_b32_e32 v39, v175
	v_mov_b32_e32 v40, v176
	v_mov_b32_e32 v41, v177
	v_lshlrev_b32_e32 v44, 16, v34
	v_add_f32_e32 v30, v30, v44
	v_and_b32_e32 v34, 0xffff0000, v34
	v_lshlrev_b32_e32 v44, 16, v36
	v_and_b32_e32 v36, 0xffff0000, v36
	v_add_f32_e32 v31, v31, v34
	v_lshlrev_b32_e32 v34, 16, v35
	v_add_f32_e32 v27, v27, v36
	v_lshlrev_b32_e32 v36, 16, v37
	v_add_f32_e32 v32, v32, v34
	v_and_b32_e32 v34, 0xffff0000, v35
	v_add_f32_e32 v28, v28, v36
	v_and_b32_e32 v36, 0xffff0000, v37
	v_add_f32_e32 v33, v33, v34
	v_cvt_pk_bf16_f32 v34, v30, v31
	v_cvt_pk_bf16_f32 v35, v32, v33
	v_add_f32_e32 v26, v26, v44
	v_add_f32_e32 v29, v29, v36
	v_cvt_pk_bf16_f32 v36, v26, v27
	v_cvt_pk_bf16_f32 v37, v28, v29
	global_store_dwordx4 v[42:43], v[34:37], off
	s_nop 0
	s_nop 0
	v_lshlrev_b32_e32 v34, 16, v38
	v_lshlrev_b32_e32 v36, 16, v40
	v_add_f32_e32 v22, v22, v34
	v_and_b32_e32 v34, 0xffff0000, v38
	v_add_f32_e32 v18, v18, v36
	v_and_b32_e32 v36, 0xffff0000, v40
	v_add_f32_e32 v23, v23, v34
	v_lshlrev_b32_e32 v34, 16, v39
	v_add_f32_e32 v19, v19, v36
	v_lshlrev_b32_e32 v36, 16, v41
	v_add_f32_e32 v24, v24, v34
	v_and_b32_e32 v34, 0xffff0000, v39
	v_add_f32_e32 v20, v20, v36
	v_and_b32_e32 v36, 0xffff0000, v41
	v_add_f32_e32 v25, v25, v34
	v_add_f32_e32 v21, v21, v36
	v_cvt_pk_bf16_f32 v34, v22, v23
	v_cvt_pk_bf16_f32 v35, v24, v25
	v_cvt_pk_bf16_f32 v36, v18, v19
	v_cvt_pk_bf16_f32 v37, v20, v21
	global_store_dwordx4 v[42:43], v[34:37], off offset:256
	s_cbranch_vccnz .LBB0_254
	v_mul_f32_e32 v31, v31, v31
	v_mul_f32_e32 v27, v27, v27
	v_mul_f32_e32 v19, v19, v19
	v_fmac_f32_e32 v31, v30, v30
	v_mul_f32_e32 v30, v33, v33
	v_fmac_f32_e32 v27, v26, v26
	v_mul_f32_e32 v26, v29, v29
	v_mul_f32_e32 v23, v23, v23
	v_fmac_f32_e32 v19, v18, v18
	v_mul_f32_e32 v18, v21, v21
	v_fmac_f32_e32 v30, v32, v32
	v_fmac_f32_e32 v26, v28, v28
	v_fmac_f32_e32 v23, v22, v22
	v_mul_f32_e32 v22, v25, v25
	v_fmac_f32_e32 v18, v20, v20
	v_add_f32_e32 v30, v31, v30
	v_add_f32_e32 v26, v27, v26
	v_fmac_f32_e32 v22, v24, v24
	v_add_f32_e32 v18, v19, v18
	v_xor_b32_e32 v19, 16, v235
	v_add_u32_e32 v20, 64, v236
	v_add_f32_e32 v26, v30, v26
	v_add_f32_e32 v22, v23, v22
	v_cmp_lt_i32_e32 vcc, v19, v20
	v_add_f32_e32 v22, v26, v22
	v_add_f32_e32 v18, v18, v22
	v_cndmask_b32_e32 v19, v235, v19, vcc
	v_lshlrev_b32_e32 v19, 2, v19
	ds_bpermute_b32 v19, v19, v18
	s_waitcnt lgkmcnt(0)
	v_add_f32_e32 v18, v18, v19
	v_xor_b32_e32 v19, 32, v235
	v_cmp_lt_i32_e32 vcc, v19, v20
	s_nop 1
	v_cndmask_b32_e32 v19, v235, v19, vcc
	v_lshlrev_b32_e32 v19, 2, v19
	ds_bpermute_b32 v19, v19, v18
	s_and_saveexec_b64 s[8:9], s[40:41]
	s_cbranch_execz .LBB0_253
	s_waitcnt lgkmcnt(0)
	v_add_f32_e32 v18, v18, v19
	v_fma_f32 v18, v18, s88, 0.5
	v_trunc_f32_e32 v18, v18
	v_mul_f32_e32 v19, 0x2f800000, v18
	v_floor_f32_e32 v19, v19
	v_fmac_f32_e32 v18, 0xcf800000, v19
	v_cvt_u32_f32_e32 v18, v18
	v_cvt_u32_f32_e32 v19, v19
	v_lshl_add_u64 v[20:21], v[140:141], 3, s[36:37]
	global_atomic_add_x2 v[20:21], v[18:19], off offset:1280

; __device__ __forceinline__ unsigned cvt_pk_bf16(float lo, float hi) { unsigned r; asm volatile("v_cvt_pk_bf16_f32 %0, %1, %2" : "=v"(r) : "v"(lo), "v"(hi)); return r; }
;     __device__ __forceinline__ void operator()(const f32x4 (&acc)[2][2][4][2], const Unit& u, int wr, int wc, int fr, int fq) const {
;         const int col0 = u.pn * BM + wc * 32 + 8 * fq;
; #pragma unroll
;         for (int ai = 0; ai < 2; ++ai)
; #pragma unroll
;             for (int m = 0; m < 4; ++m) { const int row = u.pm * BM + ai * HALF + wr * 64 + m * 16 + fr; bf16_t* xp = x + (size_t)row * ldc + col0;
;                 u32x4 bv[2];
; #pragma unroll
;                 for (int bj = 0; bj < 2; ++bj) bv[bj] = *(const u32x4*)(xp + bj * HALF);
;                 float sq = 0.f;
; #pragma unroll
;                 for (int bj = 0; bj < 2; ++bj) { u32x4 w;
; #pragma unroll
;                     for (int n = 0; n < 2; ++n) { const f32x4 a = acc[ai][bj][m][n]; const unsigned b0 = bv[bj][2 * n], b1 = bv[bj][2 * n + 1];
;                         const float o0 = __builtin_bit_cast(float, b0 << 16) + a[0], o1 = __builtin_bit_cast(float, b0 & 0xffff0000u) + a[1];
;                         const float o2 = __builtin_bit_cast(float, b1 << 16) + a[2], o3 = __builtin_bit_cast(float, b1 & 0xffff0000u) + a[3];
;                         sq += (o0 * o0 + o1 * o1) + (o2 * o2 + o3 * o3);
;                         w[2 * n] = cvt_pk_bf16(o0, o1); w[2 * n + 1] = cvt_pk_bf16(o2, o3); }
;                     *(u32x4*)(xp + bj * HALF) = w; }
;                 if (ss) { sq += __shfl_xor(sq, 16); sq += __shfl_xor(sq, 32); if (fq == 0) __hip_atomic_fetch_add(ss + row, (unsigned long long)(sq * 262144.f + 0.5f), __ATOMIC_RELAXED, __HIP_MEMORY_SCOPE_AGENT); } }
.LBB0_254:
	v_add_u32_e32 v18, 0xb0, v140
	s_waitcnt lgkmcnt(0)
	v_ashrrev_i32_e32 v19, 31, v18
	v_lshlrev_b64 v[18:19], 12, v[18:19]
	v_lshl_add_u64 v[18:19], s[18:19], 0, v[18:19]
	v_lshl_add_u64 v[26:27], v[142:143], 1, v[18:19]
	s_and_b64 vcc, exec, s[44:45]
	s_waitcnt vmcnt(10)
	v_mov_b32_e32 v18, v178
	v_mov_b32_e32 v19, v179
	v_mov_b32_e32 v20, v180
	v_mov_b32_e32 v21, v181
	v_mov_b32_e32 v22, v182
	v_mov_b32_e32 v23, v183
	v_mov_b32_e32 v24, v184
	v_mov_b32_e32 v25, v185
	v_lshlrev_b32_e32 v28, 16, v18
	v_add_f32_e32 v14, v14, v28
	v_and_b32_e32 v18, 0xffff0000, v18
	v_lshlrev_b32_e32 v28, 16, v20
	v_and_b32_e32 v20, 0xffff0000, v20
	v_add_f32_e32 v15, v15, v18
	v_lshlrev_b32_e32 v18, 16, v19
	v_add_f32_e32 v11, v11, v20
	v_lshlrev_b32_e32 v20, 16, v21
	v_add_f32_e32 v16, v16, v18
	v_and_b32_e32 v18, 0xffff0000, v19
	v_add_f32_e32 v12, v12, v20
	v_and_b32_e32 v20, 0xffff0000, v21
	v_add_f32_e32 v17, v17, v18
	v_cvt_pk_bf16_f32 v18, v14, v15
	v_cvt_pk_bf16_f32 v19, v16, v17
	v_add_f32_e32 v10, v10, v28
	v_add_f32_e32 v13, v13, v20
	v_cvt_pk_bf16_f32 v20, v10, v11
	v_cvt_pk_bf16_f32 v21, v12, v13
	global_store_dwordx4 v[26:27], v[18:21], off
	s_nop 0
	s_nop 0
	v_lshlrev_b32_e32 v18, 16, v22
	v_lshlrev_b32_e32 v20, 16, v24
	v_add_f32_e32 v6, v6, v18
	v_and_b32_e32 v18, 0xffff0000, v22
	v_add_f32_e32 v2, v2, v20
	v_and_b32_e32 v20, 0xffff0000, v24
	v_add_f32_e32 v7, v7, v18
	v_lshlrev_b32_e32 v18, 16, v23
	v_add_f32_e32 v3, v3, v20
	v_lshlrev_b32_e32 v20, 16, v25
	v_add_f32_e32 v8, v8, v18
	v_and_b32_e32 v18, 0xffff0000, v23
	v_add_f32_e32 v4, v4, v20
	v_and_b32_e32 v20, 0xffff0000, v25
	v_add_f32_e32 v9, v9, v18
	v_add_f32_e32 v5, v5, v20
	v_cvt_pk_bf16_f32 v18, v6, v7
	v_cvt_pk_bf16_f32 v19, v8, v9
	v_cvt_pk_bf16_f32 v20, v2, v3
	v_cvt_pk_bf16_f32 v21, v4, v5
	global_store_dwordx4 v[26:27], v[18:21], off offset:256
	s_cbranch_vccnz .LBB0_258
	v_mul_f32_e32 v15, v15, v15
	v_mul_f32_e32 v11, v11, v11
	v_mul_f32_e32 v3, v3, v3
	v_fmac_f32_e32 v15, v14, v14
	v_mul_f32_e32 v14, v17, v17
	v_fmac_f32_e32 v11, v10, v10
	v_mul_f32_e32 v10, v13, v13
	v_mul_f32_e32 v7, v7, v7
	v_fmac_f32_e32 v3, v2, v2
	v_mul_f32_e32 v2, v5, v5
	v_fmac_f32_e32 v14, v16, v16
	v_fmac_f32_e32 v10, v12, v12
	v_fmac_f32_e32 v7, v6, v6
	v_mul_f32_e32 v6, v9, v9
	v_fmac_f32_e32 v2, v4, v4
	v_add_f32_e32 v14, v15, v14
	v_add_f32_e32 v10, v11, v10
	v_fmac_f32_e32 v6, v8, v8
	v_add_f32_e32 v2, v3, v2
	v_xor_b32_e32 v3, 16, v235
	v_add_u32_e32 v4, 64, v236
	v_add_f32_e32 v10, v14, v10
	v_add_f32_e32 v6, v7, v6
	v_cmp_lt_i32_e32 vcc, v3, v4
	v_add_f32_e32 v6, v10, v6
	v_add_f32_e32 v2, v2, v6
	v_cndmask_b32_e32 v3, v235, v3, vcc
	v_lshlrev_b32_e32 v3, 2, v3
	ds_bpermute_b32 v3, v3, v2
	s_waitcnt lgkmcnt(0)
	v_add_f32_e32 v2, v2, v3
	v_xor_b32_e32 v3, 32, v235
	v_cmp_lt_i32_e32 vcc, v3, v4
	s_nop 1
	v_cndmask_b32_e32 v3, v235, v3, vcc
	v_lshlrev_b32_e32 v3, 2, v3
	ds_bpermute_b32 v3, v3, v2
	s_and_saveexec_b64 s[8:9], s[40:41]
	s_cbranch_execz .LBB0_257
	s_waitcnt lgkmcnt(0)
	v_add_f32_e32 v2, v2, v3
	v_fma_f32 v2, v2, s88, 0.5
	v_trunc_f32_e32 v2, v2
	v_mul_f32_e32 v3, 0x2f800000, v2
	v_floor_f32_e32 v3, v3
	v_fmac_f32_e32 v2, 0xcf800000, v3
	v_cvt_u32_f32_e32 v2, v2
	v_cvt_u32_f32_e32 v3, v3
	v_lshl_add_u64 v[4:5], v[140:141], 3, s[36:37]
	global_atomic_add_x2 v[4:5], v[2:3], off offset:1408

; #define LAS __attribute__((address_space(3)))
; template <int PH>
; DI void gla_unit(LAS char* lds, int unit, const bf16* PROJ, const float* W2, const float* gb, bf16* SC, float* DEC, const float* cnorm, bf16* MIXED, bf16* QG, bf16* KG) {
;     ...
;         { const bf16* qg = QG + (row0 + t) * 384 + 96 * h + 12 * kg; const bf16* kgp = KG + (row0 + t) * 384 + 96 * h + 12 * kg;
; #pragma unroll
;           for (int j = 0; j < 3; ++j) { *(LAS u32x2*)(lds + G_QT + t * PQK + (12 * kg + 4 * j) * 2) = *(const u32x2*)(qg + 4 * j); *(LAS u32x2*)(lds + G_KT + t * PQK + (12 * kg + 4 * j) * 2) = *(const u32x2*)(kgp + 4 * j); } }
; #pragma unroll
;         for (int j = 0; j < 3; ++j) { const int c = tid + NTHR * j, tt = c / 24, ch = c - 24 * tt;
;             *(LAS u32x4*)(lds + G_VT + tt * PV + ch * 16) = *(const u32x4*)(PROJ + (row0 + tt) * PROJP + O_VC + 192 * h + 8 * ch); }
;         const bf16* src = SC + (size_t)unit * 18432;
; #pragma unroll
;         for (int j = 0; j < 5; ++j) { const int c = tid + NTHR * j; if (c < 2304) *(LAS u32x4*)(lds + G_SP + c * 16) = *(const u32x4*)(src + c * 8); }
;         __syncthreads();
.LBB0_267:
	s_lshl_b32 s2, s1, 7
	s_and_b32 s2, s2, 0x180
	s_and_b32 s4, s1, 0xfffffe00
	s_ashr_i32 s6, s1, 9
	s_bfe_u32 s5, s1, 0x70002
	s_or_b32 s2, s2, s4
	v_mov_b32_e32 v22, v227
	s_ashr_i32 s7, s6, 31
	s_or_b32 s2, s2, s5
	s_lshl_b64 s[10:11], s[6:7], 13
	s_lshl_b32 s5, s5, 6
	v_ashrrev_i32_e32 v20, 3, v22
	s_or_b32 s10, s10, s5
	v_ashrrev_i32_e32 v21, 31, v20
	v_lshl_add_u64 v[18:19], s[10:11], 0, v[20:21]
	v_mov_b64_e32 v[2:3], s[36:37]
	v_mov_b64_e32 v[4:5], s[42:43]
	s_and_b32 s12, s1, 3
	v_and_b32_e32 v8, 7, v22
	v_mad_u64_u32 v[2:3], s[6:7], v18, s13, v[2:3]
	v_mad_u64_u32 v[4:5], s[6:7], v18, s13, v[4:5]
	v_mad_i32_i24 v3, v19, s13, v3
	s_mul_i32 s30, s12, 0xc0
	v_mul_u32_u24_e32 v0, 12, v8
	v_mad_i32_i24 v5, v19, s13, v5
	v_lshl_add_u64 v[2:3], v[2:3], 0, s[30:31]
	v_lshlrev_b32_e32 v0, 1, v0
	v_lshl_add_u64 v[4:5], v[4:5], 0, s[30:31]
	v_lshl_add_u64 v[2:3], v[2:3], 0, v[0:1]
	v_lshl_add_u64 v[6:7], v[4:5], 0, v[0:1]
	global_load_dwordx2 v[24:25], v[2:3], off offset:16
	global_load_dwordx4 v[26:29], v[2:3], off
	v_mul_u32_u24_e32 v21, 24, v8
	global_load_dwordx2 v[30:31], v[6:7], off offset:16
	global_load_dwordx4 v[32:35], v[6:7], off
	v_mul_lo_u32 v0, v20, s39
	v_add3_u32 v0, 0, v0, v21
	v_add_u32_e32 v68, 0xc000, v0
	v_add_u32_e32 v69, 0xf400, v0
	v_add_u32_e32 v70, 16, v0
	s_lshl_b32 s14, s30, 1
	s_mov_b32 s15, s31
	s_mul_hi_i32 s5, s2, 0x9000
	s_mul_i32 s2, s2, 0x9000
	v_readfirstlane_b32 s4, v22
	v_mul_hi_i32 v0, v22, s33
	v_lshrrev_b32_e32 v2, 31, v0
	v_ashrrev_i32_e32 v0, 2, v0
	v_add_u32_e32 v6, v0, v2
	v_ashrrev_i32_e32 v7, 31, v6
	v_lshl_add_u64 v[2:3], s[10:11], 0, v[6:7]
	v_mov_b64_e32 v[10:11], s[80:81]
	v_mad_u64_u32 v[4:5], s[6:7], v2, s0, v[10:11]
	v_mad_u64_u32 v[8:9], s[6:7], v6, s17, v[22:23]
	v_mad_i32_i24 v5, v3, s0, v5
	v_lshl_add_u64 v[2:3], v[4:5], 0, s[14:15]
	v_lshlrev_b32_e32 v4, 3, v8
	v_ashrrev_i32_e32 v5, 31, v4
	v_lshl_add_u64 v[2:3], v[4:5], 1, v[2:3]
	v_add_co_u32_e32 v2, vcc, s16, v2
	v_mul_lo_u32 v0, v6, s21
	s_nop 0
	v_addc_co_u32_e32 v3, vcc, 0, v3, vcc
	global_load_dwordx4 v[36:39], v[2:3], off offset:528
	v_lshlrev_b32_e32 v6, 4, v8
	v_add3_u32 v71, s22, v0, v6
	v_add_u32_e32 v0, 0x200, v22
	v_mul_hi_i32 v2, v0, s33
	v_lshrrev_b32_e32 v3, 31, v2
	v_ashrrev_i32_e32 v2, 2, v2
	v_add_u32_e32 v6, v2, v3
	v_ashrrev_i32_e32 v7, 31, v6
	v_lshl_add_u64 v[2:3], s[10:11], 0, v[6:7]
	v_mad_u64_u32 v[4:5], s[6:7], v2, s0, v[10:11]
	v_mad_u64_u32 v[8:9], s[6:7], v6, s17, v[0:1]
	v_mad_i32_i24 v5, v3, s0, v5
	v_lshl_add_u64 v[2:3], v[4:5], 0, s[14:15]
	v_lshlrev_b32_e32 v4, 3, v8
	v_ashrrev_i32_e32 v5, 31, v4
	v_lshl_add_u64 v[2:3], v[4:5], 1, v[2:3]
	v_add_co_u32_e32 v2, vcc, s16, v2
	v_mul_lo_u32 v6, v6, s21
	s_nop 0
	v_addc_co_u32_e32 v3, vcc, 0, v3, vcc
	global_load_dwordx4 v[40:43], v[2:3], off offset:528
	v_lshlrev_b32_e32 v7, 4, v8
	v_add3_u32 v72, s22, v6, v7
	v_add_u32_e32 v2, 0x400, v22
	v_mul_hi_i32 v3, v2, s33
	v_lshrrev_b32_e32 v4, 31, v3
	v_ashrrev_i32_e32 v3, 2, v3
	v_add_u32_e32 v8, v3, v4
	v_ashrrev_i32_e32 v9, 31, v8
	v_lshl_add_u64 v[4:5], s[10:11], 0, v[8:9]
	v_mad_u64_u32 v[6:7], s[6:7], v4, s0, v[10:11]
	v_mad_u64_u32 v[12:13], s[6:7], v8, s17, v[2:3]
	v_mad_i32_i24 v7, v5, s0, v7
	v_lshl_add_u64 v[4:5], v[6:7], 0, s[14:15]
	v_lshlrev_b32_e32 v6, 3, v12
	v_ashrrev_i32_e32 v7, 31, v6
	v_lshl_add_u64 v[4:5], v[6:7], 1, v[4:5]
	v_add_co_u32_e32 v4, vcc, s16, v4
	v_mul_lo_u32 v3, v8, s21
	s_nop 0
	v_addc_co_u32_e32 v5, vcc, 0, v5, vcc
	global_load_dwordx4 v[44:47], v[4:5], off offset:528
	v_lshlrev_b32_e32 v8, 4, v12
	s_add_u32 s10, s44, s2
	v_add3_u32 v73, s22, v3, v8
	s_addc_u32 s11, s45, s5
	v_lshlrev_b32_e32 v4, 3, v22
	v_ashrrev_i32_e32 v5, 31, v4
	v_lshl_add_u64 v[4:5], v[4:5], 1, s[10:11]
	global_load_dwordx4 v[48:51], v[4:5], off
	v_lshl_add_u32 v74, v22, 4, 0
	v_add_u32_e32 v74, 0x1b000, v74
	v_lshlrev_b32_e32 v4, 3, v0
	v_ashrrev_i32_e32 v5, 31, v4
	v_lshl_add_u64 v[4:5], v[4:5], 1, s[10:11]
	global_load_dwordx4 v[52:55], v[4:5], off
	v_lshl_add_u32 v75, v0, 4, 0
	v_add_u32_e32 v75, 0x1b000, v75
	v_lshlrev_b32_e32 v4, 3, v2
	v_ashrrev_i32_e32 v5, 31, v4
	v_lshl_add_u64 v[4:5], v[4:5], 1, s[10:11]
	global_load_dwordx4 v[56:59], v[4:5], off
	v_lshl_add_u32 v76, v2, 4, 0
	v_add_u32_e32 v76, 0x1b000, v76
	v_add_u32_e32 v0, 0x600, v22
	v_lshlrev_b32_e32 v4, 3, v0
	v_ashrrev_i32_e32 v5, 31, v4
	v_lshl_add_u64 v[4:5], v[4:5], 1, s[10:11]
	global_load_dwordx4 v[60:63], v[4:5], off
	v_lshl_add_u32 v77, v0, 4, 0
	v_add_u32_e32 v77, 0x1b000, v77
	s_movk_i32 s2, 0x100
	v_cmp_gt_i32_e32 vcc, s2, v22
	s_mov_b64 s[98:99], vcc
	s_and_saveexec_b64 s[14:15], vcc
	s_cbranch_execz .Lgla3_no_c4
	v_add_u32_e32 v0, 0x800, v22
	v_lshlrev_b32_e32 v4, 3, v0
	v_ashrrev_i32_e32 v5, 31, v4
	v_lshl_add_u64 v[4:5], v[4:5], 1, s[10:11]
	global_load_dwordx4 v[64:67], v[4:5], off
	v_lshl_add_u32 v78, v0, 4, 0
	v_add_u32_e32 v78, 0x1b000, v78
.Lgla3_no_c4:
	s_or_b64 exec, exec, s[14:15]
	s_waitcnt vmcnt(7)
	ds_write2_b64 v68, v[26:27], v[28:29] offset1:1
	ds_write2_b64 v69, v[32:33], v[34:35] offset1:1
	ds_write2st64_b64 v70, v[24:25], v[30:31] offset0:96 offset1:122
	s_waitcnt vmcnt(4)
	ds_write_b128 v71, v[36:39]
	ds_write_b128 v72, v[40:43]
	ds_write_b128 v73, v[44:47]
	s_waitcnt vmcnt(0)
	ds_write_b128 v74, v[48:51]
	ds_write_b128 v75, v[52:55]
	ds_write_b128 v76, v[56:59]
	ds_write_b128 v77, v[60:63]
	s_and_saveexec_b64 s[14:15], s[98:99]
	ds_write_b128 v78, v[64:67]

; #define LAS __attribute__((address_space(3)))
; __global__ void __launch_bounds__(NTHR, 2) fwd_mega(Args args) {
;     ...
;                 for (int e = tid; e < 36 * 192; e += NTHR) { const int tb_ = e / 192, st_ = e - 192 * tb_ - 32, p_ = tb_ / 12, h_ = tb_ - 12 * p_, r_ = (p_ == 0) ? 1 : (p_ == 1 ? 4 : 16); float tv = -INFINITY;
;                     if (st_ >= 0 && st_ <= 128) { const int dist = st_ * r_; int bk;
;                         if (dist < 16) bk = dist; else { bk = 16 + (int)(logf((float)dist * (1.f / 16.f)) / logf(128.f) * 16.f); bk = bk > 31 ? 31 : bk; }
;                         tv = ap->in[I_REL][bk * 12 + h_] * LOG2E; }
;                     ((LAS float*)(lds + DIL_TBLS))[e] = tv; }
;                 if (vcu < 4608) { DIL_MAKE(cur, vcu); DIL_GLOAD(cur, RG); }
;                 for (int u = vcu; u < 4608; u += G) {
.LBB0_505:
	s_or_b64 exec, exec, s[8:9]
	s_cmpk_lt_i32 s20, 0x1200
	s_cbranch_scc0 .LBB0_546
	s_mul_hi_u32 s98, s20, 0x38e38f
	s_mul_i32 s99, s98, 0x480
	s_sub_i32 s99, s20, s99
	s_mul_hi_u32 s100, s99, 0xaaaaab
	s_mul_i32 s98, s98, 0x300
	s_sub_i32 s98, s20, s98
	s_mul_i32 s100, s100, 0x480
	s_add_i32 s99, s98, s100
	s_mul_hi_i32 s4, s99, 0x2aaaaaab
	s_lshr_b32 s5, s4, 31
	s_ashr_i32 s4, s4, 8
	s_add_i32 s5, s4, s5
	s_mul_i32 s4, s5, 0xfffffa00
	s_add_i32 s4, s4, s99
	s_mul_hi_i32 s6, s4, 0x2aaaaaab
	s_lshr_b32 s7, s6, 31
	s_ashr_i32 s6, s6, 1
	s_add_i32 s7, s6, s7
	s_mul_i32 s6, s7, -12
	s_add_i32 s8, s6, s4
	s_ashr_i32 s6, s7, 5
	s_and_b32 s4, s7, 31
	s_add_i32 s7, s99, 0x5ff
	s_cmpk_lt_u32 s7, 0xbff
	s_cselect_b64 s[10:11], -1, 0
	s_add_i32 s7, s99, 0xfffffa00
	s_cmpk_lt_u32 s7, 0x600
	s_cselect_b64 s[12:13], -1, 0
	s_and_b64 s[14:15], s[12:13], exec
	s_movk_i32 s9, 0x2400
	s_cselect_b32 s7, 2, 4
	s_cselect_b32 s9, s9, 0x9000
	s_and_b64 s[14:15], s[10:11], exec
	s_cselect_b32 s14, 0, s7
	s_sub_i32 s15, 5, s14
	s_lshr_b32 s7, 32, s14
	s_lshr_b32 s15, s4, s15
	s_mul_i32 s17, s15, s7
	s_sub_i32 s16, s4, s17
	s_ashr_i32 s7, s6, 31
	s_lshl_b64 s[22:23], s[6:7], 13
	s_lshl_b32 s6, s16, 8
	s_addk_i32 s6, 0xff80
	s_ashr_i32 s7, s6, 31
	s_or_b32 s22, s22, s15
	s_lshl_b64 s[6:7], s[6:7], s14
	s_add_u32 s21, s6, s22
	s_addc_u32 s26, s7, s23
	s_lshl_b32 s14, s8, 6
	s_ashr_i32 s15, s14, 31
	s_and_b64 s[6:7], s[10:11], exec
	s_mulk_i32 s26, 0x1200
	s_mul_hi_u32 s6, s21, 0x1200
	s_cselect_b32 s7, 0x900, s9
	s_add_i32 s6, s6, s26
	s_mulk_i32 s21, 0x1200
	s_add_u32 s9, s1, s21
	s_addc_u32 s6, s2, s6
	s_lshl_b64 s[14:15], s[14:15], 1
	s_add_u32 s26, s9, s14
	s_addc_u32 s27, s6, s15
	v_lshlrev_b32_e32 v0, 3, v247
	s_cmp_eq_u32 s4, s17
	v_and_b32_e32 v0, 56, v0
	s_waitcnt vmcnt(0)
	v_mov_b32_e32 v52, v1
	v_mov_b32_e32 v53, v1
	s_cselect_b32 s4, 0x80, 0
	v_lshlrev_b32_e32 v0, 1, v0
	v_ashrrev_i32_e32 v130, 3, v247
	v_mov_b32_e32 v50, v1
	v_mov_b32_e32 v51, v1
	v_mov_b64_e32 v[56:57], v[52:53]
	v_mov_b64_e32 v[60:61], v[52:53]
	s_waitcnt lgkmcnt(0)
	v_lshl_add_u64 v[2:3], s[26:27], 0, v[0:1]
	v_cmp_le_i32_e32 vcc, s4, v130
	v_mov_b64_e32 v[54:55], v[50:51]
	v_mov_b64_e32 v[58:59], v[50:51]
	s_and_saveexec_b64 s[26:27], vcc
	s_cbranch_execz .LBB0_508
	v_mad_u64_u32 v[4:5], s[36:37], s7, v130, 0
	v_lshl_add_u64 v[4:5], v[4:5], 1, v[2:3]
	global_load_dwordx4 v[54:57], v[4:5], off offset:1536
	global_load_dwordx4 v[58:61], v[4:5], off offset:3072

; #define DIL_LWRITE(RG) do { _Pragma("unroll") for (int i_ = 0; i_ < 6; ++i_) { const int c_ = tid + NTHR * i_, row_ = c_ >> 3, ch_ = c_ & 7; \
;         *(LAS u32x4*)(lds + DIL_KB + row_ * DIL_PITCH + 16 * ch_) = RG.k[i_]; *(LAS u32x4*)(lds + DIL_VB + row_ * DIL_PITCH + 16 * ch_) = RG.v[i_]; } } while (0)
; __global__ void __launch_bounds__(NTHR, 2) fwd_mega(Args args) {
;     ...
;                 for (int u = vcu; u < 4608; u += G) {
;                     const bool has_next = (u + G < 4608);
;                     DIL_LWRITE(RG);
;                     bf16x8 qf[4];
; #pragma unroll
;                     for (int d0 = 0; d0 < 4; ++d0) qf[d0] = RG.q[d0];
;                     __syncthreads();
;                     if (has_next) { DIL_MAKE(nxt, u + G); DIL_GLOAD(nxt, RG); }
.LBB0_522:
	s_add_i32 s7, s20, s92
	s_cmpk_gt_i32 s7, 0x11ff
	s_cselect_b64 s[14:15], -1, 0
	s_and_b64 vcc, exec, s[14:15]
	s_waitcnt vmcnt(5)
	ds_write_b128 v141, v[54:57]
	s_waitcnt vmcnt(4)
	ds_write_b128 v141, v[58:61] offset:55296
	ds_write_b128 v143, v[50:53]
	ds_write_b128 v143, v[62:65] offset:55296
	ds_write_b128 v148, v[70:73]
	ds_write_b128 v148, v[74:77] offset:55296
	ds_write_b128 v149, v[66:69]
	ds_write_b128 v149, v[78:81] offset:55296
	ds_write_b128 v150, v[82:85]
	ds_write_b128 v150, v[86:89] offset:55296
	ds_write_b128 v151, v[90:93]
	ds_write_b128 v151, v[94:97] offset:55296
	s_waitcnt lgkmcnt(0)
	s_barrier
	s_cbranch_vccnz .LBB0_529
	s_mul_hi_u32 s98, s7, 0x38e38f
	s_mul_i32 s99, s98, 0x480
	s_sub_i32 s99, s7, s99
	s_mul_hi_u32 s100, s99, 0xaaaaab
	s_mul_i32 s98, s98, 0x300
	s_sub_i32 s98, s7, s98
	s_mul_i32 s100, s100, 0x480
	s_add_i32 s99, s98, s100
	s_mul_hi_i32 s10, s99, 0x2aaaaaab
	s_lshr_b32 s11, s10, 31
	s_ashr_i32 s10, s10, 8
	s_add_i32 s11, s10, s11
	s_mul_i32 s10, s11, 0xfffffa00
	s_add_i32 s10, s10, s99
	s_mul_hi_i32 s16, s10, 0x2aaaaaab
	s_lshr_b32 s17, s16, 31
	s_ashr_i32 s16, s16, 1
	s_add_i32 s16, s16, s17
	s_mul_i32 s17, s16, -12
	s_add_i32 s10, s17, s10
	s_ashr_i32 s22, s16, 5
	s_and_b32 s21, s16, 31
	s_add_i32 s16, s99, 0x5ff
	s_cmpk_lt_u32 s16, 0xbff
	s_cselect_b64 s[26:27], -1, 0
	s_add_i32 s16, s99, 0xfffffa00
	s_cmpk_lt_u32 s16, 0x600
	s_cselect_b64 s[16:17], -1, 0
	s_and_b64 s[36:37], s[16:17], exec
	s_movk_i32 s30, 0x2400
	s_cselect_b32 s23, 2, 4
	s_cselect_b32 s30, s30, 0x9000
	s_and_b64 s[36:37], s[26:27], exec
	s_cselect_b32 s37, 0, s23
	s_sub_i32 s36, 5, s37
	s_lshr_b32 s23, 32, s37
	s_lshr_b32 s44, s21, s36
	s_mul_i32 s47, s44, s23
	s_sub_i32 s36, s21, s47
	s_ashr_i32 s23, s22, 31
	s_lshl_b64 s[42:43], s[22:23], 13
	s_lshl_b32 s22, s36, 8
	s_addk_i32 s22, 0xff80
	s_ashr_i32 s23, s22, 31
	s_or_b32 s42, s42, s44
	s_lshl_b64 s[22:23], s[22:23], s37
	s_add_u32 s37, s22, s42
	s_addc_u32 s49, s23, s43
	s_lshl_b32 s22, s10, 6
	s_ashr_i32 s23, s22, 31
	s_and_b64 s[44:45], s[26:27], exec
	s_mulk_i32 s49, 0x1200
	s_mul_hi_u32 s44, s37, 0x1200
	s_cselect_b32 s30, 0x900, s30
	s_add_i32 s44, s44, s49
	s_mulk_i32 s37, 0x1200
	s_add_u32 s37, s1, s37
	s_addc_u32 s45, s2, s44
	s_lshl_b64 s[22:23], s[22:23], 1
	s_add_u32 s44, s37, s22
	s_addc_u32 s45, s45, s23
	s_cmp_eq_u32 s21, s47
	s_cselect_b32 s21, 0x80, 0
	v_lshl_add_u64 v[2:3], s[44:45], 0, v[0:1]
	v_cmp_le_i32_e32 vcc, s21, v130
	s_and_saveexec_b64 s[44:45], vcc
	s_cbranch_execz .LBB0_530
	v_mad_u64_u32 v[4:5], s[50:51], s30, v130, 0
	v_lshl_add_u64 v[4:5], v[4:5], 1, v[2:3]
	global_load_dwordx4 v[54:57], v[4:5], off offset:1536
	global_load_dwordx4 v[58:61], v[4:5], off offset:3072
	s_or_b64 exec, exec, s[44:45]
	v_cmp_le_i32_e32 vcc, s21, v132
	s_and_saveexec_b64 s[44:45], vcc
	s_cbranch_execnz .LBB0_531

; #define LAS __attribute__((address_space(3)))
; #define MFMA32(a, b, c) __builtin_amdgcn_mfma_f32_32x32x16_bf16((a), (b), (c), 0, 0, 0)
; DI void dil_compute(LAS char* lds, const DilU& u, const LAS float* tbl, int tid, const bf16x8 (&qf)[4]) {
;     ...
;     for (int a = 0; a < 5; ++a) {
;         const int s = w + a;
;         if (32 * s < u.row_lo) continue;
;         const LAS char* Kt = lds + DIL_KB + 32 * s * DIL_PITCH; const LAS char* Vt = lds + DIL_VB + 32 * s * DIL_PITCH;
;         f32x16 p;
; #pragma unroll
;         for (int r = 0; r < 16; ++r) p[r] = 0.f;
; #pragma unroll
;         for (int d0 = 0; d0 < 4; ++d0) { const bf16x8 kf = frag_row(Kt, DIL_PITCH, 0, 16 * d0, lane); p = MFMA32(kf, qf[d0], p); }
;         { const LAS float* tb = tbl + (32 + 128 + r32 - 32 * a - 4 * hi);
; #pragma unroll
;           for (int r = 0; r < 16; ++r) p[r] += tb[-((r & 3) + 8 * (r >> 2))]; }
;         float mx = p[0];
; #pragma unroll
;         for (int r = 1; r < 16; ++r) mx = fmaxf(mx, p[r]);
.LBB0_537:
	s_mul_hi_u32 s98, s20, 0x38e38f
	s_mul_i32 s99, s98, 0x480
	s_sub_i32 s99, s20, s99
	s_mul_hi_u32 s100, s99, 0xaaaaab
	s_mul_i32 s98, s98, 0x300
	s_sub_i32 s98, s20, s98
	s_mul_i32 s100, s100, 0x480
	s_add_i32 s99, s98, s100
	s_mul_hi_i32 s10, s99, 0x2aaaaaab
	s_lshr_b32 s11, s10, 31
	s_ashr_i32 s10, s10, 8
	s_add_i32 s10, s10, s11
	s_mul_i32 s11, s10, 0x600
	s_sub_i32 s11, s99, s11
	s_mul_i32 s20, s11, 0x2aab
	s_lshr_b32 s30, s20, 31
	s_lshr_b32 s20, s20, 17
	s_add_i32 s20, s20, s30
	s_mul_i32 s20, s20, 12
	s_sub_i32 s11, s11, s20
	s_sext_i32_i16 s11, s11
	v_readfirstlane_b32 s20, v247
	s_ashr_i32 s20, s20, 6
	s_mulk_i32 s10, 0x2400
	s_mulk_i32 s11, 0x300
	s_add_i32 s11, s11, s10
	s_lshl_b32 s10, s20, 5
	s_mulk_i32 s20, 0x1200
	v_add_u32_e32 v147, s11, v135
	v_add_u32_e32 v152, s20, v137
	v_add_u32_e32 v153, s20, v139
	ds_read_b128 v[2:5], v152 offset:0
	ds_read_b128 v[6:9], v152 offset:32
	ds_read_b128 v[10:13], v152 offset:64
	ds_read_b128 v[14:17], v152 offset:96
	v_add_u32_e32 v222, 0x1b214, v147
	ds_read2_b32 v[18:19], v222 offset0:27 offset1:26
	ds_read2_b32 v[20:21], v222 offset0:25 offset1:24
	ds_read2_b32 v[22:23], v222 offset0:19 offset1:18
	ds_read2_b32 v[24:25], v222 offset0:17 offset1:16
	ds_read2_b32 v[26:27], v222 offset0:11 offset1:10
	ds_read2_b32 v[28:29], v222 offset0:9 offset1:8
	ds_read2_b32 v[30:31], v222 offset0:3 offset1:2
	ds_read2_b32 v[32:33], v222 offset0:1 offset1:0
	s_waitcnt lgkmcnt(11)
	v_mfma_f32_32x32x16_bf16 v[172:187], v[2:5], v[98:101], 0
	ds_read_b128 v[2:5], v152 offset:4608
	s_waitcnt lgkmcnt(11)
	v_mfma_f32_32x32x16_bf16 v[172:187], v[6:9], v[102:105], v[172:187]
	ds_read_b128 v[6:9], v152 offset:4640
	s_waitcnt lgkmcnt(11)
	v_mfma_f32_32x32x16_bf16 v[172:187], v[10:13], v[106:109], v[172:187]
	ds_read_b128 v[10:13], v152 offset:4672
	s_waitcnt lgkmcnt(11)
	v_mfma_f32_32x32x16_bf16 v[172:187], v[14:17], v[110:113], v[172:187]
	ds_read_b128 v[14:17], v152 offset:4704
	s_waitcnt lgkmcnt(3)
	v_mfma_f32_32x32x16_bf16 v[188:203], v[2:5], v[98:101], 0
	ds_read_b128 v[2:5], v152 offset:9216
	s_waitcnt lgkmcnt(3)
	v_mfma_f32_32x32x16_bf16 v[188:203], v[6:9], v[102:105], v[188:203]
	ds_read_b128 v[6:9], v152 offset:9248
	s_waitcnt lgkmcnt(3)
	v_mfma_f32_32x32x16_bf16 v[188:203], v[10:13], v[106:109], v[188:203]
	ds_read_b128 v[10:13], v152 offset:9280
	s_waitcnt lgkmcnt(3)
	v_mfma_f32_32x32x16_bf16 v[188:203], v[14:17], v[110:113], v[188:203]
	ds_read_b128 v[14:17], v152 offset:9312
	v_add_f32_e32 v172, v172, v18
	v_add_f32_e32 v173, v173, v19
	v_add_f32_e32 v174, v174, v20
	v_add_f32_e32 v175, v175, v21
	v_add_f32_e32 v176, v176, v22
	v_add_f32_e32 v177, v177, v23
	v_add_f32_e32 v178, v178, v24
	v_add_f32_e32 v179, v179, v25
	v_add_f32_e32 v180, v180, v26
	v_add_f32_e32 v181, v181, v27
	v_add_f32_e32 v182, v182, v28
	v_add_f32_e32 v183, v183, v29
	v_add_f32_e32 v184, v184, v30
	v_add_f32_e32 v185, v185, v31
	v_add_f32_e32 v186, v186, v32
	v_add_f32_e32 v187, v187, v33
	v_add_u32_e32 v222, 0x1b194, v147
	ds_read2_b32 v[18:19], v222 offset0:27 offset1:26
	ds_read2_b32 v[20:21], v222 offset0:25 offset1:24
	ds_read2_b32 v[22:23], v222 offset0:19 offset1:18
	ds_read2_b32 v[24:25], v222 offset0:17 offset1:16
	ds_read2_b32 v[26:27], v222 offset0:11 offset1:10
	ds_read2_b32 v[28:29], v222 offset0:9 offset1:8
	ds_read2_b32 v[30:31], v222 offset0:3 offset1:2
	ds_read2_b32 v[32:33], v222 offset0:1 offset1:0
	v_max3_f32 v170, v172, v173, v174
	v_max3_f32 v170, v170, v175, v176
	v_max3_f32 v170, v170, v177, v178
	v_max3_f32 v170, v170, v179, v180
	v_max3_f32 v170, v170, v181, v182
	v_max3_f32 v170, v170, v183, v184
	v_max3_f32 v170, v170, v185, v186
	v_max_f32_e32 v170, v170, v187
	s_waitcnt lgkmcnt(11)
	v_mfma_f32_32x32x16_bf16 v[204:219], v[2:5], v[98:101], 0
	ds_read_b128 v[2:5], v152 offset:13824
	s_waitcnt lgkmcnt(11)
	v_mfma_f32_32x32x16_bf16 v[204:219], v[6:9], v[102:105], v[204:219]
	ds_read_b128 v[6:9], v152 offset:13856
	s_waitcnt lgkmcnt(11)
	v_mfma_f32_32x32x16_bf16 v[204:219], v[10:13], v[106:109], v[204:219]
	ds_read_b128 v[10:13], v152 offset:13888
	s_waitcnt lgkmcnt(11)
	v_mfma_f32_32x32x16_bf16 v[204:219], v[14:17], v[110:113], v[204:219]
	ds_read_b128 v[14:17], v152 offset:13920
	s_waitcnt lgkmcnt(4)
	v_add_f32_e32 v188, v188, v18
	v_add_f32_e32 v189, v189, v19
	v_add_f32_e32 v190, v190, v20
	v_add_f32_e32 v191, v191, v21
	v_add_f32_e32 v192, v192, v22
	v_add_f32_e32 v193, v193, v23
	v_add_f32_e32 v194, v194, v24
	v_add_f32_e32 v195, v195, v25
	v_add_f32_e32 v196, v196, v26
	v_add_f32_e32 v197, v197, v27
	v_add_f32_e32 v198, v198, v28
	v_add_f32_e32 v199, v199, v29
	v_add_f32_e32 v200, v200, v30
	v_add_f32_e32 v201, v201, v31
	v_add_f32_e32 v202, v202, v32
	v_add_f32_e32 v203, v203, v33
	v_add_u32_e32 v222, 0x1b114, v147
	ds_read2_b32 v[18:19], v222 offset0:27 offset1:26
	ds_read2_b32 v[20:21], v222 offset0:25 offset1:24
	ds_read2_b32 v[22:23], v222 offset0:19 offset1:18
	ds_read2_b32 v[24:25], v222 offset0:17 offset1:16
	ds_read2_b32 v[26:27], v222 offset0:11 offset1:10
	ds_read2_b32 v[28:29], v222 offset0:9 offset1:8
	ds_read2_b32 v[30:31], v222 offset0:3 offset1:2
	ds_read2_b32 v[32:33], v222 offset0:1 offset1:0
	v_max3_f32 v171, v188, v189, v190
	v_max3_f32 v171, v171, v191, v192
	v_max3_f32 v171, v171, v193, v194
	v_max3_f32 v171, v171, v195, v196
	v_max3_f32 v171, v171, v197, v198
	v_max3_f32 v171, v171, v199, v200
	v_max3_f32 v171, v171, v201, v202
	v_max_f32_e32 v171, v171, v203
	s_waitcnt lgkmcnt(11)
	v_mfma_f32_32x32x16_bf16 v[154:169], v[2:5], v[98:101], 0
	ds_read_b128 v[2:5], v152 offset:18432
	s_waitcnt lgkmcnt(11)
; #define LAS __attribute__((address_space(3)))
; #define MFMA32(a, b, c) __builtin_amdgcn_mfma_f32_32x32x16_bf16((a), (b), (c), 0, 0, 0)
; DI void dil_compute(LAS char* lds, const DilU& u, const LAS float* tbl, int tid, const bf16x8 (&qf)[4]) {
;     ...
;     for (int a = 0; a < 5; ++a) {
;         const int s = w + a;
;         if (32 * s < u.row_lo) continue;
;         const LAS char* Kt = lds + DIL_KB + 32 * s * DIL_PITCH; const LAS char* Vt = lds + DIL_VB + 32 * s * DIL_PITCH;
;         f32x16 p;
; #pragma unroll
;         for (int r = 0; r < 16; ++r) p[r] = 0.f;
; #pragma unroll
;         for (int d0 = 0; d0 < 4; ++d0) { const bf16x8 kf = frag_row(Kt, DIL_PITCH, 0, 16 * d0, lane); p = MFMA32(kf, qf[d0], p); }
;         { const LAS float* tb = tbl + (32 + 128 + r32 - 32 * a - 4 * hi);
; #pragma unroll
;           for (int r = 0; r < 16; ++r) p[r] += tb[-((r & 3) + 8 * (r >> 2))]; }
;         float mx = p[0];
; #pragma unroll
;         for (int r = 1; r < 16; ++r) mx = fmaxf(mx, p[r]);
	v_mfma_f32_32x32x16_bf16 v[154:169], v[6:9], v[102:105], v[154:169]
	ds_read_b128 v[6:9], v152 offset:18464
	s_waitcnt lgkmcnt(11)
	v_mfma_f32_32x32x16_bf16 v[154:169], v[10:13], v[106:109], v[154:169]
	ds_read_b128 v[10:13], v152 offset:18496
	s_waitcnt lgkmcnt(11)
	v_mfma_f32_32x32x16_bf16 v[154:169], v[14:17], v[110:113], v[154:169]
	ds_read_b128 v[14:17], v152 offset:18528
	s_waitcnt lgkmcnt(4)
	v_add_f32_e32 v204, v204, v18
	v_add_f32_e32 v205, v205, v19
	v_add_f32_e32 v206, v206, v20
	v_add_f32_e32 v207, v207, v21
	v_add_f32_e32 v208, v208, v22
	v_add_f32_e32 v209, v209, v23
	v_add_f32_e32 v210, v210, v24
	v_add_f32_e32 v211, v211, v25
	v_add_f32_e32 v212, v212, v26
	v_add_f32_e32 v213, v213, v27
	v_add_f32_e32 v214, v214, v28
	v_add_f32_e32 v215, v215, v29
	v_add_f32_e32 v216, v216, v30
	v_add_f32_e32 v217, v217, v31
	v_add_f32_e32 v218, v218, v32
	v_add_f32_e32 v219, v219, v33
	v_add_u32_e32 v222, 0x1b094, v147
	ds_read2_b32 v[18:19], v222 offset0:27 offset1:26
	ds_read2_b32 v[20:21], v222 offset0:25 offset1:24
	ds_read2_b32 v[22:23], v222 offset0:19 offset1:18
	ds_read2_b32 v[24:25], v222 offset0:17 offset1:16
	ds_read2_b32 v[26:27], v222 offset0:11 offset1:10
	ds_read2_b32 v[28:29], v222 offset0:9 offset1:8
	ds_read2_b32 v[30:31], v222 offset0:3 offset1:2
	ds_read2_b32 v[32:33], v222 offset0:1 offset1:0
	v_max3_f32 v220, v204, v205, v206
	v_max3_f32 v220, v220, v207, v208
	v_max3_f32 v220, v220, v209, v210
	v_max3_f32 v220, v220, v211, v212
	v_max3_f32 v220, v220, v213, v214
	v_max3_f32 v220, v220, v215, v216
	v_max3_f32 v220, v220, v217, v218
	v_max_f32_e32 v220, v220, v219
	s_waitcnt lgkmcnt(11)
	v_mfma_f32_32x32x16_bf16 v[34:49], v[2:5], v[98:101], 0
	s_waitcnt lgkmcnt(10)
	v_mfma_f32_32x32x16_bf16 v[34:49], v[6:9], v[102:105], v[34:49]
	s_waitcnt lgkmcnt(9)
	v_mfma_f32_32x32x16_bf16 v[34:49], v[10:13], v[106:109], v[34:49]
	s_waitcnt lgkmcnt(8)
	v_mfma_f32_32x32x16_bf16 v[34:49], v[14:17], v[110:113], v[34:49]
	s_waitcnt lgkmcnt(0)
	v_add_u32_e32 v222, 0x1b014, v147
	ds_read2_b32 v[2:3], v222 offset0:27 offset1:26
	ds_read2_b32 v[4:5], v222 offset0:25 offset1:24
	ds_read2_b32 v[6:7], v222 offset0:19 offset1:18
	ds_read2_b32 v[8:9], v222 offset0:17 offset1:16
	ds_read2_b32 v[10:11], v222 offset0:11 offset1:10
	ds_read2_b32 v[12:13], v222 offset0:9 offset1:8
	ds_read2_b32 v[14:15], v222 offset0:3 offset1:2
	ds_read2_b32 v[16:17], v222 offset0:1 offset1:0
	v_add_f32_e32 v154, v154, v18
	v_add_f32_e32 v155, v155, v19
	v_add_f32_e32 v156, v156, v20
	v_add_f32_e32 v157, v157, v21
	v_add_f32_e32 v158, v158, v22
	v_add_f32_e32 v159, v159, v23
	v_add_f32_e32 v160, v160, v24
	v_add_f32_e32 v161, v161, v25
	v_add_f32_e32 v162, v162, v26
	v_add_f32_e32 v163, v163, v27
	v_add_f32_e32 v164, v164, v28
	v_add_f32_e32 v165, v165, v29
	v_add_f32_e32 v166, v166, v30
	v_add_f32_e32 v167, v167, v31
	v_add_f32_e32 v168, v168, v32
	v_add_f32_e32 v169, v169, v33
	v_max3_f32 v221, v154, v155, v156
	v_max3_f32 v221, v221, v157, v158
	v_max3_f32 v221, v221, v159, v160
	v_max3_f32 v221, v221, v161, v162
	v_max3_f32 v221, v221, v163, v164
	v_max3_f32 v221, v221, v165, v166
	v_max3_f32 v221, v221, v167, v168
	v_max_f32_e32 v221, v221, v169
	s_waitcnt lgkmcnt(0)
	v_add_f32_e32 v34, v34, v2
	v_add_f32_e32 v35, v35, v3
	v_add_f32_e32 v36, v36, v4
	v_add_f32_e32 v37, v37, v5
	v_add_f32_e32 v38, v38, v6
	v_add_f32_e32 v39, v39, v7
	v_add_f32_e32 v40, v40, v8
	v_add_f32_e32 v41, v41, v9
	v_add_f32_e32 v42, v42, v10
	v_add_f32_e32 v43, v43, v11
	v_add_f32_e32 v44, v44, v12
	v_add_f32_e32 v45, v45, v13
	v_add_f32_e32 v46, v46, v14
	v_add_f32_e32 v47, v47, v15
	v_add_f32_e32 v48, v48, v16
	v_add_f32_e32 v49, v49, v17
	v_max3_f32 v223, v34, v35, v36
	v_max3_f32 v223, v223, v37, v38
	v_max3_f32 v223, v223, v39, v40
	v_max3_f32 v223, v223, v41, v42
	v_max3_f32 v223, v223, v43, v44
	v_max3_f32 v223, v223, v45, v46
	v_max3_f32 v223, v223, v47, v48
	v_max_f32_e32 v223, v223, v49
	s_cmp_lt_i32 s10, s4
	s_cbranch_scc0 .Ldil_nomask
	v_mov_b32_e32 v170, 0xff800000
	v_mov_b32_e32 v172, v170
	v_mov_b32_e32 v173, v170
	v_mov_b32_e32 v174, v170
	v_mov_b32_e32 v175, v170
	v_mov_b32_e32 v176, v170
	v_mov_b32_e32 v177, v170
	v_mov_b32_e32 v178, v170
	v_mov_b32_e32 v179, v170
	v_mov_b32_e32 v180, v170
	v_mov_b32_e32 v181, v170
	v_mov_b32_e32 v182, v170
	v_mov_b32_e32 v183, v170
	v_mov_b32_e32 v184, v170
	v_mov_b32_e32 v185, v170
	v_mov_b32_e32 v186, v170
	v_mov_b32_e32 v187, v170
	s_add_i32 s98, s10, 32
	s_cmp_lt_i32 s98, s4
	s_cbranch_scc0 .Ldil_nomask
	v_mov_b32_e32 v171, 0xff800000
	v_mov_b32_e32 v188, v171
	v_mov_b32_e32 v189, v171
	v_mov_b32_e32 v190, v171
	v_mov_b32_e32 v191, v171
	v_mov_b32_e32 v192, v171
	v_mov_b32_e32 v193, v171
	v_mov_b32_e32 v194, v171
	v_mov_b32_e32 v195, v171
	v_mov_b32_e32 v196, v171
	v_mov_b32_e32 v197, v171
	v_mov_b32_e32 v198, v171
	v_mov_b32_e32 v199, v171
	v_mov_b32_e32 v200, v171
	v_mov_b32_e32 v201, v171
	v_mov_b32_e32 v202, v171
	v_mov_b32_e32 v203, v171
	s_add_i32 s98, s10, 64
	s_cmp_lt_i32 s98, s4
	s_cbranch_scc0 .Ldil_nomask
	v_mov_b32_e32 v220, 0xff800000
	v_mov_b32_e32 v204, v220
	v_mov_b32_e32 v205, v220
	v_mov_b32_e32 v206, v220
	v_mov_b32_e32 v207, v220
	v_mov_b32_e32 v208, v220
	v_mov_b32_e32 v209, v220
	v_mov_b32_e32 v210, v220
	v_mov_b32_e32 v211, v220
	v_mov_b32_e32 v212, v220
	v_mov_b32_e32 v213, v220
	v_mov_b32_e32 v214, v220
	v_mov_b32_e32 v215, v220
	v_mov_b32_e32 v216, v220
	v_mov_b32_e32 v217, v220
	v_mov_b32_e32 v218, v220
	v_mov_b32_e32 v219, v220
	s_add_i32 s98, s10, 96
	s_cmp_lt_i32 s98, s4
	s_cbranch_scc0 .Ldil_nomask
	v_mov_b32_e32 v221, 0xff800000
	v_mov_b32_e32 v154, v221
	v_mov_b32_e32 v155, v221
	v_mov_b32_e32 v156, v221
	v_mov_b32_e32 v157, v221
	v_mov_b32_e32 v158, v221
	v_mov_b32_e32 v159, v221
	v_mov_b32_e32 v160, v221
	v_mov_b32_e32 v161, v221
	v_mov_b32_e32 v162, v221
	v_mov_b32_e32 v163, v221
	v_mov_b32_e32 v164, v221
	v_mov_b32_e32 v165, v221
	v_mov_b32_e32 v166, v221
	v_mov_b32_e32 v167, v221
	v_mov_b32_e32 v168, v221
	v_mov_b32_e32 v169, v221

; __device__ __forceinline__ unsigned cvt_pk_bf16(float lo, float hi) { unsigned r; asm volatile("v_cvt_pk_bf16_f32 %0, %1, %2" : "=v"(r) : "v"(lo), "v"(hi)); return r; }
;     __device__ __forceinline__ void operator()(const f32x4 (&acc)[2][2][4][2], const Unit& u, int wr, int wc, int fr, int fq) const {
;     ...
;             for (int m = 0; m < 4; ++m) { bf16_t* rowp = Ob + (size_t)(row0 + ai * HALF + m * 16) * ld + col0;
;                 float rs = 1.f; if (ss) rs = __builtin_amdgcn_rsqf((float)ss[row0 + ai * HALF + m * 16] * (1.f / (2048.f * 262144.f)) + 1e-6f);
; #pragma unroll
;                 for (int bj = 0; bj < 2; ++bj) { const f32x4 v0 = acc[ai][bj][m][0] * rs, v1 = acc[ai][bj][m][1] * rs;
;                     u32x4 w; w.x = cvt_pk_bf16(v0[0], v0[1]); w.y = cvt_pk_bf16(v0[2], v0[3]); w.z = cvt_pk_bf16(v1[0], v1[1]); w.w = cvt_pk_bf16(v1[2], v1[3]);
;                     *(u32x4*)(rowp + bj * HALF) = w; } }
.LBB0_562:
	v_lshl_add_u32 v140, s42, 8, v147
	v_ashrrev_i32_e32 v141, 31, v140
	v_cndmask_b32_e64 v142, 0, 1, s[20:21]
	v_mov_b32_e32 v146, 1.0
	v_cmp_ne_u32_e64 s[42:43], 1, v142
	s_andn2_b64 vcc, exec, s[20:21]
	v_lshl_add_u64 v[142:143], v[140:141], 3, s[12:13]
	v_mov_b32_e32 v148, 1.0
	s_cbranch_vccnz .LBB0_564
	global_load_dwordx2 v[160:161], v[142:143], off
	global_load_dwordx2 v[162:163], v[142:143], off offset:128
	global_load_dwordx2 v[164:165], v[142:143], off offset:256
	global_load_dwordx2 v[166:167], v[142:143], off offset:384
	global_load_dwordx2 v[168:169], v[142:143], off offset:1024
	global_load_dwordx2 v[170:171], v[142:143], off offset:1152
	global_load_dwordx2 v[172:173], v[142:143], off offset:1280
	global_load_dwordx2 v[174:175], v[142:143], off offset:1408
	s_waitcnt vmcnt(7)
	v_mov_b32_e32 v144, v160
	v_mov_b32_e32 v145, v161
	v_ffbh_u32_e32 v141, v145
	v_min_u32_e32 v141, 32, v141
	v_lshlrev_b64 v[144:145], v141, v[144:145]
	v_min_u32_e32 v144, 1, v144
	v_or_b32_e32 v144, v145, v144
	v_cvt_f32_u32_e32 v144, v144
	v_sub_u32_e32 v141, 32, v141
	v_ldexp_f32 v141, v144, v141
	v_fmamk_f32 v141, v141, 0x31000000, v232
	v_rsq_f32_e32 v148, v141
.LBB0_564:
	s_cmp_gt_i32 s16, 8
	s_cselect_b32 s11, -9, 0
	s_movk_i32 s10, 0x900
	s_cselect_b32 s23, s81, s2
	s_cselect_b32 s37, s80, s1
	s_cselect_b32 s10, 0x1080, s10
	s_add_i32 s11, s11, s16
	v_lshl_or_b32 v144, s11, 8, v150
	v_mov_b32_e32 v152, s37
	v_mov_b32_e32 v153, s23
	v_ashrrev_i32_e32 v145, 31, v144
	v_lshl_add_u64 v[144:145], v[144:145], 1, v[152:153]
	v_mad_i64_i32 v[152:153], s[50:51], s10, v140, 0
	v_lshl_add_u64 v[152:153], v[152:153], 1, v[144:145]
	v_pk_mul_f32 v[128:129], v[128:129], v[148:149] op_sel_hi:[1,0]
	v_pk_mul_f32 v[126:127], v[126:127], v[148:149] op_sel_hi:[1,0]
	v_pk_mul_f32 v[154:155], v[124:125], v[148:149] op_sel_hi:[1,0]
	v_pk_mul_f32 v[124:125], v[122:123], v[148:149] op_sel_hi:[1,0]
	v_cvt_pk_bf16_f32 v122, v126, v127
	v_cvt_pk_bf16_f32 v123, v128, v129
	s_and_b64 vcc, exec, s[42:43]
	v_cvt_pk_bf16_f32 v124, v124, v125
	v_cvt_pk_bf16_f32 v125, v154, v155
	global_store_dwordx4 v[152:153], v[122:125], off
	v_pk_mul_f32 v[120:121], v[120:121], v[148:149] op_sel_hi:[1,0]
	v_pk_mul_f32 v[118:119], v[118:119], v[148:149] op_sel_hi:[1,0]
	v_pk_mul_f32 v[122:123], v[116:117], v[148:149] op_sel_hi:[1,0]
	v_pk_mul_f32 v[116:117], v[114:115], v[148:149] op_sel_hi:[1,0]
	v_cvt_pk_bf16_f32 v114, v118, v119
	v_cvt_pk_bf16_f32 v115, v120, v121
	s_nop 0
	v_cvt_pk_bf16_f32 v116, v116, v117
	v_cvt_pk_bf16_f32 v117, v122, v123
	global_store_dwordx4 v[152:153], v[114:117], off offset:256
	s_cbranch_vccnz .LBB0_566
	s_waitcnt vmcnt(8)
	v_mov_b32_e32 v114, v162
	v_mov_b32_e32 v115, v163
	v_ffbh_u32_e32 v116, v115
	v_min_u32_e32 v116, 32, v116
	v_lshlrev_b64 v[114:115], v116, v[114:115]
	v_min_u32_e32 v114, 1, v114
	v_or_b32_e32 v114, v115, v114
	v_cvt_f32_u32_e32 v114, v114
	v_sub_u32_e32 v115, 32, v116
	v_ldexp_f32 v114, v114, v115
	v_fmamk_f32 v114, v114, 0x31000000, v232
	v_rsq_f32_e32 v146, v114
.LBB0_566:
	s_nop 0
	v_or_b32_e32 v114, 16, v140
	v_mad_i64_i32 v[114:115], s[50:51], s10, v114, 0
	v_lshl_add_u64 v[114:115], v[114:115], 1, v[144:145]
	v_pk_mul_f32 v[112:113], v[112:113], v[146:147] op_sel_hi:[1,0]
	v_pk_mul_f32 v[110:111], v[110:111], v[146:147] op_sel_hi:[1,0]
	v_pk_mul_f32 v[116:117], v[108:109], v[146:147] op_sel_hi:[1,0]
	v_pk_mul_f32 v[108:109], v[106:107], v[146:147] op_sel_hi:[1,0]
	v_cvt_pk_bf16_f32 v106, v110, v111
	v_cvt_pk_bf16_f32 v107, v112, v113
	v_pk_mul_f32 v[104:105], v[104:105], v[146:147] op_sel_hi:[1,0]
	v_cvt_pk_bf16_f32 v108, v108, v109
	v_cvt_pk_bf16_f32 v109, v116, v117
	global_store_dwordx4 v[114:115], v[106:109], off
	v_pk_mul_f32 v[102:103], v[102:103], v[146:147] op_sel_hi:[1,0]
	s_and_b64 vcc, exec, s[42:43]
	v_pk_mul_f32 v[106:107], v[100:101], v[146:147] op_sel_hi:[1,0]
	v_pk_mul_f32 v[100:101], v[98:99], v[146:147] op_sel_hi:[1,0]
	v_cvt_pk_bf16_f32 v98, v102, v103
	v_cvt_pk_bf16_f32 v99, v104, v105
	s_nop 0
	v_cvt_pk_bf16_f32 v100, v100, v101
	v_cvt_pk_bf16_f32 v101, v106, v107
	global_store_dwordx4 v[114:115], v[98:101], off offset:256
	s_nop 1
	v_mov_b32_e32 v98, 1.0
	v_mov_b32_e32 v100, 1.0
	s_cbranch_vccnz .LBB0_568
	s_waitcnt vmcnt(9)
	v_mov_b32_e32 v100, v164
	v_mov_b32_e32 v101, v165
	v_ffbh_u32_e32 v99, v101
	v_min_u32_e32 v99, 32, v99
	v_lshlrev_b64 v[100:101], v99, v[100:101]
	v_min_u32_e32 v100, 1, v100
	v_or_b32_e32 v100, v101, v100
	v_cvt_f32_u32_e32 v100, v100
	v_sub_u32_e32 v99, 32, v99
	v_ldexp_f32 v99, v100, v99
	v_fmamk_f32 v99, v99, 0x31000000, v232
	v_rsq_f32_e32 v100, v99
.LBB0_568:
	v_or_b32_e32 v99, 32, v140
	v_mad_i64_i32 v[102:103], s[50:51], s10, v99, 0
	v_lshl_add_u64 v[102:103], v[102:103], 1, v[144:145]
	v_pk_mul_f32 v[96:97], v[96:97], v[100:101] op_sel_hi:[1,0]
	v_pk_mul_f32 v[94:95], v[94:95], v[100:101] op_sel_hi:[1,0]
	v_pk_mul_f32 v[104:105], v[92:93], v[100:101] op_sel_hi:[1,0]
	v_pk_mul_f32 v[92:93], v[90:91], v[100:101] op_sel_hi:[1,0]
	v_cvt_pk_bf16_f32 v90, v94, v95
	v_cvt_pk_bf16_f32 v91, v96, v97
	s_and_b64 vcc, exec, s[42:43]
	v_cvt_pk_bf16_f32 v92, v92, v93
	v_cvt_pk_bf16_f32 v93, v104, v105
	global_store_dwordx4 v[102:103], v[90:93], off
	v_pk_mul_f32 v[88:89], v[88:89], v[100:101] op_sel_hi:[1,0]
	v_pk_mul_f32 v[86:87], v[86:87], v[100:101] op_sel_hi:[1,0]
	v_pk_mul_f32 v[90:91], v[84:85], v[100:101] op_sel_hi:[1,0]
	v_pk_mul_f32 v[84:85], v[82:83], v[100:101] op_sel_hi:[1,0]
	v_cvt_pk_bf16_f32 v82, v86, v87
	v_cvt_pk_bf16_f32 v83, v88, v89
	s_nop 0
	v_cvt_pk_bf16_f32 v84, v84, v85
	v_cvt_pk_bf16_f32 v85, v90, v91
	global_store_dwordx4 v[102:103], v[82:85], off offset:256
	s_cbranch_vccnz .LBB0_570
	s_waitcnt vmcnt(10)
	v_mov_b32_e32 v82, v166
	v_mov_b32_e32 v83, v167
	v_ffbh_u32_e32 v84, v83
	v_min_u32_e32 v84, 32, v84
	v_lshlrev_b64 v[82:83], v84, v[82:83]
	v_min_u32_e32 v82, 1, v82
	v_or_b32_e32 v82, v83, v82
	v_cvt_f32_u32_e32 v82, v82
	v_sub_u32_e32 v83, 32, v84
	v_ldexp_f32 v82, v82, v83
	v_fmamk_f32 v82, v82, 0x31000000, v232
	v_rsq_f32_e32 v98, v82
; __device__ __forceinline__ unsigned cvt_pk_bf16(float lo, float hi) { unsigned r; asm volatile("v_cvt_pk_bf16_f32 %0, %1, %2" : "=v"(r) : "v"(lo), "v"(hi)); return r; }
;     __device__ __forceinline__ void operator()(const f32x4 (&acc)[2][2][4][2], const Unit& u, int wr, int wc, int fr, int fq) const {
;     ...
;             for (int m = 0; m < 4; ++m) { bf16_t* rowp = Ob + (size_t)(row0 + ai * HALF + m * 16) * ld + col0;
;                 float rs = 1.f; if (ss) rs = __builtin_amdgcn_rsqf((float)ss[row0 + ai * HALF + m * 16] * (1.f / (2048.f * 262144.f)) + 1e-6f);
; #pragma unroll
;                 for (int bj = 0; bj < 2; ++bj) { const f32x4 v0 = acc[ai][bj][m][0] * rs, v1 = acc[ai][bj][m][1] * rs;
;                     u32x4 w; w.x = cvt_pk_bf16(v0[0], v0[1]); w.y = cvt_pk_bf16(v0[2], v0[3]); w.z = cvt_pk_bf16(v1[0], v1[1]); w.w = cvt_pk_bf16(v1[2], v1[3]);
;                     *(u32x4*)(rowp + bj * HALF) = w; } }
.LBB0_570:
	s_nop 0
	v_or_b32_e32 v82, 48, v140
	v_mad_i64_i32 v[82:83], s[50:51], s10, v82, 0
	v_lshl_add_u64 v[82:83], v[82:83], 1, v[144:145]
	v_pk_mul_f32 v[80:81], v[80:81], v[98:99] op_sel_hi:[1,0]
	v_pk_mul_f32 v[78:79], v[78:79], v[98:99] op_sel_hi:[1,0]
	v_pk_mul_f32 v[84:85], v[76:77], v[98:99] op_sel_hi:[1,0]
	v_pk_mul_f32 v[76:77], v[74:75], v[98:99] op_sel_hi:[1,0]
	v_cvt_pk_bf16_f32 v74, v78, v79
	v_cvt_pk_bf16_f32 v75, v80, v81
	v_pk_mul_f32 v[72:73], v[72:73], v[98:99] op_sel_hi:[1,0]
	v_cvt_pk_bf16_f32 v76, v76, v77
	v_cvt_pk_bf16_f32 v77, v84, v85
	global_store_dwordx4 v[82:83], v[74:77], off
	v_pk_mul_f32 v[70:71], v[70:71], v[98:99] op_sel_hi:[1,0]
	s_and_b64 vcc, exec, s[42:43]
	v_pk_mul_f32 v[74:75], v[68:69], v[98:99] op_sel_hi:[1,0]
	v_pk_mul_f32 v[68:69], v[66:67], v[98:99] op_sel_hi:[1,0]
	v_cvt_pk_bf16_f32 v66, v70, v71
	v_cvt_pk_bf16_f32 v67, v72, v73
	s_nop 0
	v_cvt_pk_bf16_f32 v68, v68, v69
	v_cvt_pk_bf16_f32 v69, v74, v75
	global_store_dwordx4 v[82:83], v[66:69], off offset:256
	s_nop 1
	v_mov_b32_e32 v66, 1.0
	v_mov_b32_e32 v68, 1.0
	s_cbranch_vccnz .LBB0_572
	s_waitcnt vmcnt(11)
	v_mov_b32_e32 v68, v168
	v_mov_b32_e32 v69, v169
	v_ffbh_u32_e32 v67, v69
	v_min_u32_e32 v67, 32, v67
	v_lshlrev_b64 v[68:69], v67, v[68:69]
	v_min_u32_e32 v68, 1, v68
	v_or_b32_e32 v68, v69, v68
	v_cvt_f32_u32_e32 v68, v68
	v_sub_u32_e32 v67, 32, v67
	v_ldexp_f32 v67, v68, v67
	v_fmamk_f32 v67, v67, 0x31000000, v232
	v_rsq_f32_e32 v68, v67
.LBB0_572:
	v_add_u32_e32 v67, 0x80, v140
	v_mad_i64_i32 v[70:71], s[50:51], s10, v67, 0
	v_lshl_add_u64 v[70:71], v[70:71], 1, v[144:145]
	v_pk_mul_f32 v[64:65], v[64:65], v[68:69] op_sel_hi:[1,0]
	v_pk_mul_f32 v[62:63], v[62:63], v[68:69] op_sel_hi:[1,0]
	v_pk_mul_f32 v[72:73], v[60:61], v[68:69] op_sel_hi:[1,0]
	v_pk_mul_f32 v[60:61], v[58:59], v[68:69] op_sel_hi:[1,0]
	v_cvt_pk_bf16_f32 v58, v62, v63
	v_cvt_pk_bf16_f32 v59, v64, v65
	s_and_b64 vcc, exec, s[42:43]
	v_cvt_pk_bf16_f32 v60, v60, v61
	v_cvt_pk_bf16_f32 v61, v72, v73
	global_store_dwordx4 v[70:71], v[58:61], off
	v_pk_mul_f32 v[56:57], v[56:57], v[68:69] op_sel_hi:[1,0]
	v_pk_mul_f32 v[54:55], v[54:55], v[68:69] op_sel_hi:[1,0]
	v_pk_mul_f32 v[58:59], v[52:53], v[68:69] op_sel_hi:[1,0]
	v_pk_mul_f32 v[52:53], v[50:51], v[68:69] op_sel_hi:[1,0]
	v_cvt_pk_bf16_f32 v50, v54, v55
	v_cvt_pk_bf16_f32 v51, v56, v57
	s_nop 0
	v_cvt_pk_bf16_f32 v52, v52, v53
	v_cvt_pk_bf16_f32 v53, v58, v59
	global_store_dwordx4 v[70:71], v[50:53], off offset:256
	s_cbranch_vccnz .LBB0_574
	s_waitcnt vmcnt(12)
	v_mov_b32_e32 v50, v170
	v_mov_b32_e32 v51, v171
	v_ffbh_u32_e32 v52, v51
	v_min_u32_e32 v52, 32, v52
	v_lshlrev_b64 v[50:51], v52, v[50:51]
	v_min_u32_e32 v50, 1, v50
	v_or_b32_e32 v50, v51, v50
	v_cvt_f32_u32_e32 v50, v50
	v_sub_u32_e32 v51, 32, v52
	v_ldexp_f32 v50, v50, v51
	v_fmamk_f32 v50, v50, 0x31000000, v232
	v_rsq_f32_e32 v66, v50
.LBB0_574:
	s_nop 0
	v_add_u32_e32 v50, 0x90, v140
	v_mad_i64_i32 v[50:51], s[50:51], s10, v50, 0
	v_lshl_add_u64 v[50:51], v[50:51], 1, v[144:145]
	v_pk_mul_f32 v[48:49], v[48:49], v[66:67] op_sel_hi:[1,0]
	v_pk_mul_f32 v[46:47], v[46:47], v[66:67] op_sel_hi:[1,0]
	v_pk_mul_f32 v[52:53], v[44:45], v[66:67] op_sel_hi:[1,0]
	v_pk_mul_f32 v[44:45], v[42:43], v[66:67] op_sel_hi:[1,0]
	v_cvt_pk_bf16_f32 v42, v46, v47
	v_cvt_pk_bf16_f32 v43, v48, v49
	v_pk_mul_f32 v[40:41], v[40:41], v[66:67] op_sel_hi:[1,0]
	v_cvt_pk_bf16_f32 v44, v44, v45
	v_cvt_pk_bf16_f32 v45, v52, v53
	global_store_dwordx4 v[50:51], v[42:45], off
	v_pk_mul_f32 v[38:39], v[38:39], v[66:67] op_sel_hi:[1,0]
	s_and_b64 vcc, exec, s[42:43]
	v_pk_mul_f32 v[42:43], v[36:37], v[66:67] op_sel_hi:[1,0]
	v_pk_mul_f32 v[36:37], v[34:35], v[66:67] op_sel_hi:[1,0]
	v_cvt_pk_bf16_f32 v34, v38, v39
	v_cvt_pk_bf16_f32 v35, v40, v41
	s_nop 0
	v_cvt_pk_bf16_f32 v36, v36, v37
	v_cvt_pk_bf16_f32 v37, v42, v43
	global_store_dwordx4 v[50:51], v[34:37], off offset:256
	s_nop 1
	v_mov_b32_e32 v34, 1.0
	v_mov_b32_e32 v36, 1.0
	s_cbranch_vccnz .LBB0_576
	s_waitcnt vmcnt(13)
	v_mov_b32_e32 v36, v172
	v_mov_b32_e32 v37, v173
	v_ffbh_u32_e32 v35, v37
	v_min_u32_e32 v35, 32, v35
	v_lshlrev_b64 v[36:37], v35, v[36:37]
	v_min_u32_e32 v36, 1, v36
	v_or_b32_e32 v36, v37, v36
	v_cvt_f32_u32_e32 v36, v36
	v_sub_u32_e32 v35, 32, v35
	v_ldexp_f32 v35, v36, v35
	v_fmamk_f32 v35, v35, 0x31000000, v232
	v_rsq_f32_e32 v36, v35
.LBB0_576:
	v_add_u32_e32 v35, 0xa0, v140
	v_mad_i64_i32 v[38:39], s[50:51], s10, v35, 0
	v_lshl_add_u64 v[38:39], v[38:39], 1, v[144:145]
	v_pk_mul_f32 v[32:33], v[32:33], v[36:37] op_sel_hi:[1,0]
	v_pk_mul_f32 v[30:31], v[30:31], v[36:37] op_sel_hi:[1,0]
	v_pk_mul_f32 v[40:41], v[28:29], v[36:37] op_sel_hi:[1,0]
	v_pk_mul_f32 v[28:29], v[26:27], v[36:37] op_sel_hi:[1,0]
	v_cvt_pk_bf16_f32 v26, v30, v31
	v_cvt_pk_bf16_f32 v27, v32, v33
	s_and_b64 vcc, exec, s[42:43]
	v_cvt_pk_bf16_f32 v28, v28, v29
	v_cvt_pk_bf16_f32 v29, v40, v41
	global_store_dwordx4 v[38:39], v[26:29], off
	v_pk_mul_f32 v[24:25], v[24:25], v[36:37] op_sel_hi:[1,0]
	v_pk_mul_f32 v[22:23], v[22:23], v[36:37] op_sel_hi:[1,0]
	v_pk_mul_f32 v[26:27], v[20:21], v[36:37] op_sel_hi:[1,0]
	v_pk_mul_f32 v[20:21], v[18:19], v[36:37] op_sel_hi:[1,0]
	v_cvt_pk_bf16_f32 v18, v22, v23
	v_cvt_pk_bf16_f32 v19, v24, v25
	s_nop 0
	v_cvt_pk_bf16_f32 v20, v20, v21
	v_cvt_pk_bf16_f32 v21, v26, v27
	global_store_dwordx4 v[38:39], v[18:21], off offset:256
	s_cbranch_vccnz .LBB0_578
	s_waitcnt vmcnt(14)
	v_mov_b32_e32 v18, v174
	v_mov_b32_e32 v19, v175
	v_ffbh_u32_e32 v20, v19
	v_min_u32_e32 v20, 32, v20
	v_lshlrev_b64 v[18:19], v20, v[18:19]
	v_min_u32_e32 v18, 1, v18
	v_or_b32_e32 v18, v19, v18
	v_cvt_f32_u32_e32 v18, v18
	v_sub_u32_e32 v19, 32, v20
	v_ldexp_f32 v18, v18, v19
	v_fmamk_f32 v18, v18, 0x31000000, v232
	v_rsq_f32_e32 v34, v18

; __global__ void __launch_bounds__(NTHR, 2) fwd_mega(Args args) {
	.amdhsa_kernel _Z8fwd_mega4Args
		.amdhsa_group_segment_fixed_size 0
		.amdhsa_private_segment_fixed_size 0
		.amdhsa_kernarg_size 448
		.amdhsa_user_sgpr_count 2
		.amdhsa_user_sgpr_dispatch_ptr 0
		.amdhsa_user_sgpr_queue_ptr 0
		.amdhsa_user_sgpr_kernarg_segment_ptr 1
		.amdhsa_user_sgpr_dispatch_id 0
		.amdhsa_user_sgpr_kernarg_preload_length 0
		.amdhsa_user_sgpr_kernarg_preload_offset 0
		.amdhsa_user_sgpr_private_segment_size 0
		.amdhsa_uses_dynamic_stack 0
		.amdhsa_enable_private_segment 0
		.amdhsa_system_sgpr_workgroup_id_x 1
		.amdhsa_system_sgpr_workgroup_id_y 0
		.amdhsa_system_sgpr_workgroup_id_z 0
		.amdhsa_system_sgpr_workgroup_info 0
		.amdhsa_system_vgpr_workitem_id 2
		.amdhsa_next_free_vgpr 256
		.amdhsa_next_free_sgpr 101
		.amdhsa_accum_offset 256
		.amdhsa_reserve_vcc 1
		.amdhsa_float_round_mode_32 0
		.amdhsa_float_round_mode_16_64 0
		.amdhsa_float_denorm_mode_32 3
		.amdhsa_float_denorm_mode_16_64 3
		.amdhsa_dx10_clamp 1
		.amdhsa_ieee_mode 1
		.amdhsa_fp16_overflow 0
		.amdhsa_tg_split 0
		.amdhsa_exception_fp_ieee_invalid_op 0
		.amdhsa_exception_fp_denorm_src 0
		.amdhsa_exception_fp_ieee_div_zero 0
		.amdhsa_exception_fp_ieee_overflow 0
		.amdhsa_exception_fp_ieee_underflow 0
		.amdhsa_exception_fp_ieee_inexact 0
		.amdhsa_exception_int_div_zero 0
	.end_amdhsa_kernel

; __global__ void __launch_bounds__(NTHR, 2) fwd_mega(Args args) {
amdhsa.kernels:
  - .agpr_count:     0
    .args:
      - .offset:         0
        .size:           192
        .value_kind:     by_value
      - .offset:         192
        .size:           4
        .value_kind:     hidden_block_count_x
      - .offset:         196
        .size:           4
        .value_kind:     hidden_block_count_y
      - .offset:         200
        .size:           4
        .value_kind:     hidden_block_count_z
      - .offset:         204
        .size:           2
        .value_kind:     hidden_group_size_x
      - .offset:         206
        .size:           2
        .value_kind:     hidden_group_size_y
      - .offset:         208
        .size:           2
        .value_kind:     hidden_group_size_z
      - .offset:         210
        .size:           2
        .value_kind:     hidden_remainder_x
      - .offset:         212
        .size:           2
        .value_kind:     hidden_remainder_y
      - .offset:         214
        .size:           2
        .value_kind:     hidden_remainder_z
      - .offset:         232
        .size:           8
        .value_kind:     hidden_global_offset_x
      - .offset:         240
        .size:           8
        .value_kind:     hidden_global_offset_y
      - .offset:         248
        .size:           8
        .value_kind:     hidden_global_offset_z
      - .offset:         256
        .size:           2
        .value_kind:     hidden_grid_dims
      - .offset:         280
        .size:           8
        .value_kind:     hidden_multigrid_sync_arg
      - .offset:         312
        .size:           4
        .value_kind:     hidden_dynamic_lds_size
    .group_segment_fixed_size: 0
    .kernarg_segment_align: 8
    .kernarg_segment_size: 448
    .language:       OpenCL C
    .language_version:
      - 2
      - 0
    .max_flat_workgroup_size: 512
    .name:           _Z8fwd_mega4Args
    .private_segment_fixed_size: 0
    .sgpr_count:     107
    .sgpr_spill_count: 158
    .symbol:         _Z8fwd_mega4Args.kd
    .uniform_work_group_size: 1
    .uses_dynamic_stack: false
    .vgpr_count:     256
    .vgpr_spill_count: 0
    .wavefront_size: 64
